# v17 plus: gate/up panel-counter increment deferred to the next unit's K-loop end (no per-unit store drain) and counted waits instead of store drains in the RG-LRU gate epilogue
# speedup vs baseline: 1.0119x; 1.0021x over previous
; __device__ __forceinline__ unsigned cvt_pk_bf16(float lo, float hi) { unsigned r; asm volatile("v_cvt_pk_bf16_f32 %0, %1, %2" : "=v"(r) : "v"(lo), "v"(hi)); return r; }
; __device__ __forceinline__ float bflo(unsigned w) { return __uint_as_float(w << 16); }
; __device__ __forceinline__ float bfhi(unsigned w) { return __uint_as_float(w & 0xffff0000u); }
; __device__ __forceinline__ float fsigmoid(float x) { return __builtin_amdgcn_rcpf(1.0f + __expf(-x)); }
;     __device__ __forceinline__ void operator()(const f32x4 (&acc)[2][2][4][2], const Unit& u, int wr, int wc, int fr, int fq) const {
;     ...
;             for (int ai = 0; ai < 2; ++ai) { u32x2 xq[4];
; #pragma unroll
;                 for (int m = 0; m < 4; ++m) { const int row = row0 + ai * 128 + m * 16; xq[m] = *(const u32x2*)(XC + (size_t)(row < TT ? row : TT - 1) * DRNN + ch0 + 16 * n); }
; #pragma unroll
;                 for (int m = 0; m < 4; ++m) { const int row = row0 + ai * 128 + m * 16;
;                     if (row < TT) { const size_t off = (size_t)row * DRNN + ch0 + 16 * n; const u32x2 xw = xq[m]; const f32x4 xc = (f32x4){bflo(xw.x), bfhi(xw.x), bflo(xw.y), bfhi(xw.y)}; u32x4 o;
; #pragma unroll
;                         for (int i = 0; i < 4; ++i) { const float r = fsigmoid(acc[ai][0][m][n][i] + ba[i]), ig = fsigmoid(acc[ai][1][m][n][i] + bx[i]);
;                             const float la = r * lv[i], x2 = la + la, m = x2 > -1e-3f ? -x2 * fmaf(x2, 0.5f, 1.0f) : 1.0f - __expf(x2);
;                             o[i] = cvt_pk_bf16(la, __builtin_amdgcn_sqrtf(fmaxf(m, 0.0f)) * ig * xc[i]); }
;                         *(u32x4*)(AB + off) = o; } }
;                 asm volatile("" ::: "memory"); } }
.LBB0_780:
	s_waitcnt vmcnt(1)
	v_add_f32_e32 v128, v128, v96
	v_mul_f32_e32 v128, 0xbfb8aa3b, v128
	v_exp_f32_e32 v128, v128
	s_nop 0
	v_add_f32_e32 v128, 1.0, v128
	v_rcp_f32_e32 v128, v128
	s_nop 0
	v_mul_f32_e32 v128, v92, v128
	v_add_f32_e32 v133, v128, v128
	v_cmp_nlt_f32_e64 s[44:45], s95, v133
	s_and_saveexec_b64 s[34:35], s[44:45]
	s_xor_b64 s[36:37], exec, s[34:35]
	v_mul_f32_e32 v132, 0x3fb8aa3b, v133
	v_exp_f32_e32 v132, v132
	s_nop 0
	v_sub_f32_e32 v132, 1.0, v132
	s_andn2_saveexec_b64 s[36:37], s[36:37]
	v_fma_f32 v132, v133, 0.5, 1.0
	v_mul_f32_e64 v132, v132, -v133
	s_or_b64 exec, exec, s[36:37]
	v_add_f32_e32 v124, v124, v88
	v_mul_f32_e32 v124, 0xbfb8aa3b, v124
	v_exp_f32_e32 v124, v124
	v_add_f32_e32 v129, v129, v97
	v_mul_f32_e32 v129, 0xbfb8aa3b, v129
	v_exp_f32_e32 v129, v129
	v_max_f32_e32 v132, v132, v132
	v_add_f32_e32 v124, 1.0, v124
	v_max_f32_e32 v132, 0, v132
	v_rcp_f32_e32 v124, v124
	v_sqrt_f32_e32 v132, v132
	v_add_f32_e32 v129, 1.0, v129
	v_rcp_f32_e32 v129, v129
	v_lshlrev_b32_e32 v133, 16, v168
	v_mul_f32_e32 v124, v124, v132
	v_mul_f32_e32 v124, v124, v133
	v_cvt_pk_bf16_f32 v124, v128, v124
	v_mul_f32_e32 v128, v93, v129
	v_add_f32_e32 v132, v128, v128
	v_cmp_nlt_f32_e64 s[44:45], s95, v132
	s_and_saveexec_b64 s[34:35], s[44:45]
	s_xor_b64 s[36:37], exec, s[34:35]
	v_mul_f32_e32 v129, 0x3fb8aa3b, v132
	v_exp_f32_e32 v129, v129
	s_nop 0
	v_sub_f32_e32 v129, 1.0, v129
	s_andn2_saveexec_b64 s[36:37], s[36:37]
	v_fma_f32 v129, v132, 0.5, 1.0
	v_mul_f32_e64 v129, v129, -v132
	s_or_b64 exec, exec, s[36:37]
	v_add_f32_e32 v125, v125, v89
	v_mul_f32_e32 v125, 0xbfb8aa3b, v125
	v_exp_f32_e32 v125, v125
	v_add_f32_e32 v130, v130, v98
	v_mul_f32_e32 v130, 0xbfb8aa3b, v130
	v_exp_f32_e32 v130, v130
	v_max_f32_e32 v129, v129, v129
	v_add_f32_e32 v125, 1.0, v125
	v_max_f32_e32 v129, 0, v129
	v_rcp_f32_e32 v125, v125
	v_sqrt_f32_e32 v129, v129
	v_add_f32_e32 v130, 1.0, v130
	v_rcp_f32_e32 v130, v130
	v_and_b32_e32 v132, 0xffff0000, v168
	v_mul_f32_e32 v125, v125, v129
	v_mul_f32_e32 v125, v125, v132
	v_cvt_pk_bf16_f32 v125, v128, v125
	v_mul_f32_e32 v128, v94, v130
	v_add_f32_e32 v130, v128, v128
	v_cmp_nlt_f32_e64 s[44:45], s95, v130
	s_and_saveexec_b64 s[34:35], s[44:45]
	s_xor_b64 s[36:37], exec, s[34:35]
	v_mul_f32_e32 v129, 0x3fb8aa3b, v130
	v_exp_f32_e32 v129, v129
	s_nop 0
	v_sub_f32_e32 v129, 1.0, v129
	s_andn2_saveexec_b64 s[36:37], s[36:37]
	v_fma_f32 v129, v130, 0.5, 1.0
	v_mul_f32_e64 v129, v129, -v130
	s_or_b64 exec, exec, s[36:37]
	v_add_f32_e32 v126, v126, v90
	v_mul_f32_e32 v126, 0xbfb8aa3b, v126
	v_exp_f32_e32 v126, v126
	v_add_f32_e32 v130, v131, v99
	v_mul_f32_e32 v130, 0xbfb8aa3b, v130
	v_exp_f32_e32 v130, v130
	v_max_f32_e32 v129, v129, v129
	v_add_f32_e32 v126, 1.0, v126
	v_max_f32_e32 v129, 0, v129
	v_rcp_f32_e32 v126, v126
	v_sqrt_f32_e32 v129, v129
	v_add_f32_e32 v130, 1.0, v130
	v_rcp_f32_e32 v130, v130
	v_lshlrev_b32_e32 v131, 16, v169
	v_mul_f32_e32 v126, v126, v129
	v_mul_f32_e32 v126, v126, v131
	v_cvt_pk_bf16_f32 v126, v128, v126
	v_mul_f32_e32 v128, v95, v130
	v_add_f32_e32 v130, v128, v128
	v_cmp_nlt_f32_e64 s[44:45], s95, v130
	s_and_saveexec_b64 s[34:35], s[44:45]
	s_xor_b64 s[36:37], exec, s[34:35]
	v_mul_f32_e32 v129, 0x3fb8aa3b, v130
	v_exp_f32_e32 v129, v129
	s_nop 0
	v_sub_f32_e32 v129, 1.0, v129
	s_andn2_saveexec_b64 s[36:37], s[36:37]
	v_fma_f32 v129, v130, 0.5, 1.0
	v_mul_f32_e64 v129, v129, -v130
	s_or_b64 exec, exec, s[36:37]
	v_add_f32_e32 v127, v127, v91
	v_mul_f32_e32 v127, 0xbfb8aa3b, v127
	v_exp_f32_e32 v127, v127
	v_max_f32_e32 v129, v129, v129
	v_max_f32_e32 v129, 0, v129
	v_sqrt_f32_e32 v129, v129
	v_add_f32_e32 v127, 1.0, v127
	v_rcp_f32_e32 v127, v127
	v_and_b32_e32 v130, 0xffff0000, v169
	v_mul_f32_e32 v127, v127, v129
	v_mul_f32_e32 v127, v127, v130
	v_cvt_pk_bf16_f32 v127, v128, v127
	v_mov_b64_e32 v[128:129], s[62:63]
	v_mad_i64_i32 v[128:129], s[34:35], v195, s87, v[128:129]
	v_lshl_add_u64 v[128:129], v[146:147], 2, v[128:129]
	global_store_dwordx4 v[128:129], v[124:127], off
	s_or_b64 exec, exec, s[22:23]
	v_cmp_gt_i32_e64 s[44:45], s6, v194
	s_and_saveexec_b64 s[22:23], s[44:45]
	s_cbranch_execz .LBB0_762
.LBB0_797:
	s_waitcnt vmcnt(2)
	v_add_f32_e32 v120, v120, v96
	v_mul_f32_e32 v120, 0xbfb8aa3b, v120
	v_exp_f32_e32 v120, v120
	s_nop 0
	v_add_f32_e32 v120, 1.0, v120
	v_rcp_f32_e32 v120, v120
	s_nop 0
	v_mul_f32_e32 v120, v92, v120
	v_add_f32_e32 v125, v120, v120
	v_cmp_nlt_f32_e64 s[46:47], s95, v125
	s_and_saveexec_b64 s[34:35], s[46:47]
	s_xor_b64 s[36:37], exec, s[34:35]
	v_mul_f32_e32 v124, 0x3fb8aa3b, v125
	v_exp_f32_e32 v124, v124
	s_nop 0
	v_sub_f32_e32 v124, 1.0, v124
	s_andn2_saveexec_b64 s[36:37], s[36:37]
	v_fma_f32 v124, v125, 0.5, 1.0
	v_mul_f32_e64 v124, v124, -v125
	s_or_b64 exec, exec, s[36:37]
	v_add_f32_e32 v116, v116, v88
	v_mul_f32_e32 v116, 0xbfb8aa3b, v116
	v_exp_f32_e32 v116, v116
	v_add_f32_e32 v121, v121, v97
	v_mul_f32_e32 v121, 0xbfb8aa3b, v121
	v_exp_f32_e32 v121, v121
	v_max_f32_e32 v124, v124, v124
	v_add_f32_e32 v116, 1.0, v116
	v_max_f32_e32 v124, 0, v124
	v_rcp_f32_e32 v116, v116
	v_sqrt_f32_e32 v124, v124
	v_add_f32_e32 v121, 1.0, v121
	v_rcp_f32_e32 v121, v121
	v_lshlrev_b32_e32 v125, 16, v166
	v_mul_f32_e32 v116, v116, v124
	v_mul_f32_e32 v116, v116, v125
	v_cvt_pk_bf16_f32 v116, v120, v116
	v_mul_f32_e32 v120, v93, v121
	v_add_f32_e32 v124, v120, v120
	v_cmp_nlt_f32_e64 s[46:47], s95, v124
	s_and_saveexec_b64 s[34:35], s[46:47]
	s_xor_b64 s[36:37], exec, s[34:35]
	v_mul_f32_e32 v121, 0x3fb8aa3b, v124
	v_exp_f32_e32 v121, v121
	s_nop 0
	v_sub_f32_e32 v121, 1.0, v121
	s_andn2_saveexec_b64 s[36:37], s[36:37]
; __device__ __forceinline__ unsigned cvt_pk_bf16(float lo, float hi) { unsigned r; asm volatile("v_cvt_pk_bf16_f32 %0, %1, %2" : "=v"(r) : "v"(lo), "v"(hi)); return r; }
; __device__ __forceinline__ float bflo(unsigned w) { return __uint_as_float(w << 16); }
; __device__ __forceinline__ float bfhi(unsigned w) { return __uint_as_float(w & 0xffff0000u); }
; __device__ __forceinline__ float fsigmoid(float x) { return __builtin_amdgcn_rcpf(1.0f + __expf(-x)); }
;     __device__ __forceinline__ void operator()(const f32x4 (&acc)[2][2][4][2], const Unit& u, int wr, int wc, int fr, int fq) const {
;     ...
;             for (int ai = 0; ai < 2; ++ai) { u32x2 xq[4];
; #pragma unroll
;                 for (int m = 0; m < 4; ++m) { const int row = row0 + ai * 128 + m * 16; xq[m] = *(const u32x2*)(XC + (size_t)(row < TT ? row : TT - 1) * DRNN + ch0 + 16 * n); }
; #pragma unroll
;                 for (int m = 0; m < 4; ++m) { const int row = row0 + ai * 128 + m * 16;
;                     if (row < TT) { const size_t off = (size_t)row * DRNN + ch0 + 16 * n; const u32x2 xw = xq[m]; const f32x4 xc = (f32x4){bflo(xw.x), bfhi(xw.x), bflo(xw.y), bfhi(xw.y)}; u32x4 o;
; #pragma unroll
;                         for (int i = 0; i < 4; ++i) { const float r = fsigmoid(acc[ai][0][m][n][i] + ba[i]), ig = fsigmoid(acc[ai][1][m][n][i] + bx[i]);
;                             const float la = r * lv[i], x2 = la + la, m = x2 > -1e-3f ? -x2 * fmaf(x2, 0.5f, 1.0f) : 1.0f - __expf(x2);
;                             o[i] = cvt_pk_bf16(la, __builtin_amdgcn_sqrtf(fmaxf(m, 0.0f)) * ig * xc[i]); }
;                         *(u32x4*)(AB + off) = o; } }
;                 asm volatile("" ::: "memory"); } }
	v_fma_f32 v121, v124, 0.5, 1.0
	v_mul_f32_e64 v121, v121, -v124
	s_or_b64 exec, exec, s[36:37]
	v_add_f32_e32 v117, v117, v89
	v_mul_f32_e32 v117, 0xbfb8aa3b, v117
	v_exp_f32_e32 v117, v117
	v_add_f32_e32 v122, v122, v98
	v_mul_f32_e32 v122, 0xbfb8aa3b, v122
	v_exp_f32_e32 v122, v122
	v_max_f32_e32 v121, v121, v121
	v_add_f32_e32 v117, 1.0, v117
	v_max_f32_e32 v121, 0, v121
	v_rcp_f32_e32 v117, v117
	v_sqrt_f32_e32 v121, v121
	v_add_f32_e32 v122, 1.0, v122
	v_rcp_f32_e32 v122, v122
	v_and_b32_e32 v124, 0xffff0000, v166
	v_mul_f32_e32 v117, v117, v121
	v_mul_f32_e32 v117, v117, v124
	v_cvt_pk_bf16_f32 v117, v120, v117
	v_mul_f32_e32 v120, v94, v122
	v_add_f32_e32 v122, v120, v120
	v_cmp_nlt_f32_e64 s[46:47], s95, v122
	s_and_saveexec_b64 s[34:35], s[46:47]
	s_xor_b64 s[36:37], exec, s[34:35]
	v_mul_f32_e32 v121, 0x3fb8aa3b, v122
	v_exp_f32_e32 v121, v121
	s_nop 0
	v_sub_f32_e32 v121, 1.0, v121
	s_andn2_saveexec_b64 s[36:37], s[36:37]
	v_fma_f32 v121, v122, 0.5, 1.0
	v_mul_f32_e64 v121, v121, -v122
	s_or_b64 exec, exec, s[36:37]
	v_add_f32_e32 v118, v118, v90
	v_mul_f32_e32 v118, 0xbfb8aa3b, v118
	v_exp_f32_e32 v118, v118
	v_add_f32_e32 v122, v123, v99
	v_mul_f32_e32 v122, 0xbfb8aa3b, v122
	v_exp_f32_e32 v122, v122
	v_max_f32_e32 v121, v121, v121
	v_add_f32_e32 v118, 1.0, v118
	v_max_f32_e32 v121, 0, v121
	v_rcp_f32_e32 v118, v118
	v_sqrt_f32_e32 v121, v121
	v_add_f32_e32 v122, 1.0, v122
	v_rcp_f32_e32 v122, v122
	v_lshlrev_b32_e32 v123, 16, v167
	v_mul_f32_e32 v118, v118, v121
	v_mul_f32_e32 v118, v118, v123
	v_cvt_pk_bf16_f32 v118, v120, v118
	v_mul_f32_e32 v120, v95, v122
	v_add_f32_e32 v122, v120, v120
	v_cmp_nlt_f32_e64 s[46:47], s95, v122
	s_and_saveexec_b64 s[34:35], s[46:47]
	s_xor_b64 s[36:37], exec, s[34:35]
	v_mul_f32_e32 v121, 0x3fb8aa3b, v122
	v_exp_f32_e32 v121, v121
	s_nop 0
	v_sub_f32_e32 v121, 1.0, v121
	s_andn2_saveexec_b64 s[36:37], s[36:37]
	v_fma_f32 v121, v122, 0.5, 1.0
	v_mul_f32_e64 v121, v121, -v122
	s_or_b64 exec, exec, s[36:37]
	v_add_f32_e32 v119, v119, v91
	v_mul_f32_e32 v119, 0xbfb8aa3b, v119
	v_exp_f32_e32 v119, v119
	v_max_f32_e32 v121, v121, v121
	v_max_f32_e32 v121, 0, v121
	v_sqrt_f32_e32 v121, v121
	v_add_f32_e32 v119, 1.0, v119
	v_rcp_f32_e32 v119, v119
	v_and_b32_e32 v122, 0xffff0000, v167
	v_mul_f32_e32 v119, v119, v121
	v_mul_f32_e32 v119, v119, v122
	v_cvt_pk_bf16_f32 v119, v120, v119
	v_mov_b64_e32 v[120:121], s[62:63]
	v_mad_i64_i32 v[120:121], s[34:35], v194, s87, v[120:121]
	v_lshl_add_u64 v[120:121], v[146:147], 2, v[120:121]
	global_store_dwordx4 v[120:121], v[116:119], off
	s_or_b64 exec, exec, s[22:23]
	v_cmp_gt_i32_e64 s[46:47], s6, v193
	s_and_saveexec_b64 s[22:23], s[46:47]
	s_cbranch_execz .LBB0_831
.LBB0_814:
	s_waitcnt vmcnt(3)
	v_add_f32_e32 v112, v112, v96
	v_mul_f32_e32 v112, 0xbfb8aa3b, v112
	v_exp_f32_e32 v112, v112
	s_nop 0
	v_add_f32_e32 v112, 1.0, v112
	v_rcp_f32_e32 v112, v112
	s_nop 0
	v_mul_f32_e32 v112, v92, v112
	v_add_f32_e32 v117, v112, v112
	v_cmp_nlt_f32_e64 s[48:49], s95, v117
	s_and_saveexec_b64 s[34:35], s[48:49]
	s_xor_b64 s[36:37], exec, s[34:35]
	v_mul_f32_e32 v116, 0x3fb8aa3b, v117
	v_exp_f32_e32 v116, v116
	s_nop 0
	v_sub_f32_e32 v116, 1.0, v116
	s_andn2_saveexec_b64 s[36:37], s[36:37]
	v_fma_f32 v116, v117, 0.5, 1.0
	v_mul_f32_e64 v116, v116, -v117
	s_or_b64 exec, exec, s[36:37]
	v_add_f32_e32 v108, v108, v88
	v_mul_f32_e32 v108, 0xbfb8aa3b, v108
	v_exp_f32_e32 v108, v108
	v_add_f32_e32 v113, v113, v97
	v_mul_f32_e32 v113, 0xbfb8aa3b, v113
	v_exp_f32_e32 v113, v113
	v_max_f32_e32 v116, v116, v116
	v_add_f32_e32 v108, 1.0, v108
	v_max_f32_e32 v116, 0, v116
	v_rcp_f32_e32 v108, v108
	v_sqrt_f32_e32 v116, v116
	v_add_f32_e32 v113, 1.0, v113
	v_rcp_f32_e32 v113, v113
	v_lshlrev_b32_e32 v117, 16, v164
	v_mul_f32_e32 v108, v108, v116
	v_mul_f32_e32 v108, v108, v117
	v_cvt_pk_bf16_f32 v108, v112, v108
	v_mul_f32_e32 v112, v93, v113
	v_add_f32_e32 v116, v112, v112
	v_cmp_nlt_f32_e64 s[48:49], s95, v116
	s_and_saveexec_b64 s[34:35], s[48:49]
	s_xor_b64 s[36:37], exec, s[34:35]
	v_mul_f32_e32 v113, 0x3fb8aa3b, v116
	v_exp_f32_e32 v113, v113
	s_nop 0
	v_sub_f32_e32 v113, 1.0, v113
	s_andn2_saveexec_b64 s[36:37], s[36:37]
	v_fma_f32 v113, v116, 0.5, 1.0
	v_mul_f32_e64 v113, v113, -v116
	s_or_b64 exec, exec, s[36:37]
	v_add_f32_e32 v109, v109, v89
	v_mul_f32_e32 v109, 0xbfb8aa3b, v109
	v_exp_f32_e32 v109, v109
	v_add_f32_e32 v114, v114, v98
	v_mul_f32_e32 v114, 0xbfb8aa3b, v114
	v_exp_f32_e32 v114, v114
	v_max_f32_e32 v113, v113, v113
	v_add_f32_e32 v109, 1.0, v109
	v_max_f32_e32 v113, 0, v113
	v_rcp_f32_e32 v109, v109
	v_sqrt_f32_e32 v113, v113
	v_add_f32_e32 v114, 1.0, v114
	v_rcp_f32_e32 v114, v114
	v_and_b32_e32 v116, 0xffff0000, v164
	v_mul_f32_e32 v109, v109, v113
	v_mul_f32_e32 v109, v109, v116
	v_cvt_pk_bf16_f32 v109, v112, v109
	v_mul_f32_e32 v112, v94, v114
	v_add_f32_e32 v114, v112, v112
	v_cmp_nlt_f32_e64 s[48:49], s95, v114
	s_and_saveexec_b64 s[34:35], s[48:49]
	s_xor_b64 s[36:37], exec, s[34:35]
	v_mul_f32_e32 v113, 0x3fb8aa3b, v114
	v_exp_f32_e32 v113, v113
	s_nop 0
	v_sub_f32_e32 v113, 1.0, v113
	s_andn2_saveexec_b64 s[36:37], s[36:37]
	v_fma_f32 v113, v114, 0.5, 1.0
	v_mul_f32_e64 v113, v113, -v114
	s_or_b64 exec, exec, s[36:37]
	v_add_f32_e32 v110, v110, v90
	v_mul_f32_e32 v110, 0xbfb8aa3b, v110
	v_exp_f32_e32 v110, v110
	v_add_f32_e32 v114, v115, v99
	v_mul_f32_e32 v114, 0xbfb8aa3b, v114
	v_exp_f32_e32 v114, v114
	v_max_f32_e32 v113, v113, v113
	v_add_f32_e32 v110, 1.0, v110
	v_max_f32_e32 v113, 0, v113
	v_rcp_f32_e32 v110, v110
	v_sqrt_f32_e32 v113, v113
	v_add_f32_e32 v114, 1.0, v114
	v_rcp_f32_e32 v114, v114
	v_lshlrev_b32_e32 v115, 16, v165
	v_mul_f32_e32 v110, v110, v113
	v_mul_f32_e32 v110, v110, v115
	v_cvt_pk_bf16_f32 v110, v112, v110
	v_mul_f32_e32 v112, v95, v114
	v_add_f32_e32 v114, v112, v112
	v_cmp_nlt_f32_e64 s[48:49], s95, v114
	s_and_saveexec_b64 s[34:35], s[48:49]
	s_xor_b64 s[36:37], exec, s[34:35]
	v_mul_f32_e32 v113, 0x3fb8aa3b, v114
	v_exp_f32_e32 v113, v113
	s_nop 0
	v_sub_f32_e32 v113, 1.0, v113
	s_andn2_saveexec_b64 s[36:37], s[36:37]
	v_fma_f32 v113, v114, 0.5, 1.0
	v_mul_f32_e64 v113, v113, -v114
	s_or_b64 exec, exec, s[36:37]
	v_add_f32_e32 v111, v111, v91
	v_mul_f32_e32 v111, 0xbfb8aa3b, v111
	v_exp_f32_e32 v111, v111
	v_max_f32_e32 v113, v113, v113
	v_max_f32_e32 v113, 0, v113
	v_sqrt_f32_e32 v113, v113
	v_add_f32_e32 v111, 1.0, v111
	v_rcp_f32_e32 v111, v111
	v_and_b32_e32 v114, 0xffff0000, v165
	v_mul_f32_e32 v111, v111, v113
	v_mul_f32_e32 v111, v111, v114
	v_cvt_pk_bf16_f32 v111, v112, v111
	v_mov_b64_e32 v[112:113], s[62:63]
	v_mad_i64_i32 v[112:113], s[34:35], v193, s87, v[112:113]
	v_lshl_add_u64 v[112:113], v[146:147], 2, v[112:113]
	global_store_dwordx4 v[112:113], v[108:111], off

; __device__ __forceinline__ unsigned cvt_pk_bf16(float lo, float hi) { unsigned r; asm volatile("v_cvt_pk_bf16_f32 %0, %1, %2" : "=v"(r) : "v"(lo), "v"(hi)); return r; }
; __device__ __forceinline__ float bflo(unsigned w) { return __uint_as_float(w << 16); }
; __device__ __forceinline__ float bfhi(unsigned w) { return __uint_as_float(w & 0xffff0000u); }
; __device__ __forceinline__ float fsigmoid(float x) { return __builtin_amdgcn_rcpf(1.0f + __expf(-x)); }
;     __device__ __forceinline__ void operator()(const f32x4 (&acc)[2][2][4][2], const Unit& u, int wr, int wc, int fr, int fq) const {
;     ...
;             for (int ai = 0; ai < 2; ++ai) { u32x2 xq[4];
; #pragma unroll
;                 for (int m = 0; m < 4; ++m) { const int row = row0 + ai * 128 + m * 16; xq[m] = *(const u32x2*)(XC + (size_t)(row < TT ? row : TT - 1) * DRNN + ch0 + 16 * n); }
; #pragma unroll
;                 for (int m = 0; m < 4; ++m) { const int row = row0 + ai * 128 + m * 16;
;                     if (row < TT) { const size_t off = (size_t)row * DRNN + ch0 + 16 * n; const u32x2 xw = xq[m]; const f32x4 xc = (f32x4){bflo(xw.x), bfhi(xw.x), bflo(xw.y), bfhi(xw.y)}; u32x4 o;
; #pragma unroll
;                         for (int i = 0; i < 4; ++i) { const float r = fsigmoid(acc[ai][0][m][n][i] + ba[i]), ig = fsigmoid(acc[ai][1][m][n][i] + bx[i]);
;                             const float la = r * lv[i], x2 = la + la, m = x2 > -1e-3f ? -x2 * fmaf(x2, 0.5f, 1.0f) : 1.0f - __expf(x2);
;                             o[i] = cvt_pk_bf16(la, __builtin_amdgcn_sqrtf(fmaxf(m, 0.0f)) * ig * xc[i]); }
;                         *(u32x4*)(AB + off) = o; } }
;                 asm volatile("" ::: "memory"); } }
.LBB0_849:
	s_or_b64 exec, exec, s[22:23]
	s_movk_i32 s6, 0x1ff0
	v_cmp_gt_i32_e64 s[50:51], s6, v196
	s_and_saveexec_b64 s[22:23], s[50:51]
	s_cbranch_execz .LBB0_867
	s_waitcnt vmcnt(1)
	v_add_f32_e32 v84, v84, v96
	v_mul_f32_e32 v84, 0xbfb8aa3b, v84
	v_exp_f32_e32 v84, v84
	s_nop 0
	v_add_f32_e32 v84, 1.0, v84
	v_rcp_f32_e32 v84, v84
	s_nop 0
	v_mul_f32_e32 v84, v92, v84
	v_add_f32_e32 v101, v84, v84
	v_cmp_nlt_f32_e64 s[52:53], s95, v101
	s_and_saveexec_b64 s[34:35], s[52:53]
	s_xor_b64 s[36:37], exec, s[34:35]
	v_mul_f32_e32 v100, 0x3fb8aa3b, v101
	v_exp_f32_e32 v100, v100
	s_nop 0
	v_sub_f32_e32 v100, 1.0, v100
	s_andn2_saveexec_b64 s[36:37], s[36:37]
	v_fma_f32 v100, v101, 0.5, 1.0
	v_mul_f32_e64 v100, v100, -v101
	s_or_b64 exec, exec, s[36:37]
	v_add_f32_e32 v80, v80, v88
	v_mul_f32_e32 v80, 0xbfb8aa3b, v80
	v_exp_f32_e32 v80, v80
	v_add_f32_e32 v85, v85, v97
	v_mul_f32_e32 v85, 0xbfb8aa3b, v85
	v_exp_f32_e32 v85, v85
	v_max_f32_e32 v100, v100, v100
	v_add_f32_e32 v80, 1.0, v80
	v_max_f32_e32 v100, 0, v100
	v_rcp_f32_e32 v80, v80
	v_sqrt_f32_e32 v100, v100
	v_add_f32_e32 v85, 1.0, v85
	v_rcp_f32_e32 v85, v85
	v_lshlrev_b32_e32 v101, 16, v120
	v_mul_f32_e32 v80, v80, v100
	v_mul_f32_e32 v80, v80, v101
	v_cvt_pk_bf16_f32 v80, v84, v80
	v_mul_f32_e32 v84, v93, v85
	v_add_f32_e32 v100, v84, v84
	v_cmp_nlt_f32_e64 s[52:53], s95, v100
	s_and_saveexec_b64 s[34:35], s[52:53]
	s_xor_b64 s[36:37], exec, s[34:35]
	v_mul_f32_e32 v85, 0x3fb8aa3b, v100
	v_exp_f32_e32 v85, v85
	s_nop 0
	v_sub_f32_e32 v85, 1.0, v85
	s_andn2_saveexec_b64 s[36:37], s[36:37]
	v_fma_f32 v85, v100, 0.5, 1.0
	v_mul_f32_e64 v85, v85, -v100
	s_or_b64 exec, exec, s[36:37]
	v_add_f32_e32 v81, v81, v89
	v_mul_f32_e32 v81, 0xbfb8aa3b, v81
	v_exp_f32_e32 v81, v81
	v_add_f32_e32 v86, v86, v98
	v_mul_f32_e32 v86, 0xbfb8aa3b, v86
	v_exp_f32_e32 v86, v86
	v_max_f32_e32 v85, v85, v85
	v_add_f32_e32 v81, 1.0, v81
	v_max_f32_e32 v85, 0, v85
	v_rcp_f32_e32 v81, v81
	v_sqrt_f32_e32 v85, v85
	v_add_f32_e32 v86, 1.0, v86
	v_rcp_f32_e32 v86, v86
	v_and_b32_e32 v100, 0xffff0000, v120
	v_mul_f32_e32 v81, v81, v85
	v_mul_f32_e32 v81, v81, v100
	v_cvt_pk_bf16_f32 v81, v84, v81
	v_mul_f32_e32 v84, v94, v86
	v_add_f32_e32 v86, v84, v84
	v_cmp_nlt_f32_e64 s[52:53], s95, v86
	s_and_saveexec_b64 s[34:35], s[52:53]
	s_xor_b64 s[36:37], exec, s[34:35]
	v_mul_f32_e32 v85, 0x3fb8aa3b, v86
	v_exp_f32_e32 v85, v85
	s_nop 0
	v_sub_f32_e32 v85, 1.0, v85
	s_andn2_saveexec_b64 s[36:37], s[36:37]
	v_fma_f32 v85, v86, 0.5, 1.0
	v_mul_f32_e64 v85, v85, -v86
	s_or_b64 exec, exec, s[36:37]
	v_add_f32_e32 v82, v82, v90
	v_mul_f32_e32 v82, 0xbfb8aa3b, v82
	v_exp_f32_e32 v82, v82
	v_add_f32_e32 v86, v87, v99
	v_mul_f32_e32 v86, 0xbfb8aa3b, v86
	v_exp_f32_e32 v86, v86
	v_max_f32_e32 v85, v85, v85
	v_add_f32_e32 v82, 1.0, v82
	v_max_f32_e32 v85, 0, v85
	v_rcp_f32_e32 v82, v82
	v_sqrt_f32_e32 v85, v85
	v_add_f32_e32 v86, 1.0, v86
	v_rcp_f32_e32 v86, v86
	v_lshlrev_b32_e32 v87, 16, v121
	v_mul_f32_e32 v82, v82, v85
	v_mul_f32_e32 v82, v82, v87
	v_cvt_pk_bf16_f32 v82, v84, v82
	v_mul_f32_e32 v84, v95, v86
	v_add_f32_e32 v86, v84, v84
	v_cmp_nlt_f32_e64 s[52:53], s95, v86
	s_and_saveexec_b64 s[34:35], s[52:53]
	s_xor_b64 s[36:37], exec, s[34:35]
	v_mul_f32_e32 v85, 0x3fb8aa3b, v86
	v_exp_f32_e32 v85, v85
	s_nop 0
	v_sub_f32_e32 v85, 1.0, v85
	s_andn2_saveexec_b64 s[36:37], s[36:37]
	v_fma_f32 v85, v86, 0.5, 1.0
	v_mul_f32_e64 v85, v85, -v86
	s_or_b64 exec, exec, s[36:37]
	v_add_f32_e32 v83, v83, v91
	v_mul_f32_e32 v83, 0xbfb8aa3b, v83
	v_exp_f32_e32 v83, v83
	v_max_f32_e32 v85, v85, v85
	v_max_f32_e32 v85, 0, v85
	v_sqrt_f32_e32 v85, v85
	v_add_f32_e32 v83, 1.0, v83
	v_rcp_f32_e32 v83, v83
	v_and_b32_e32 v86, 0xffff0000, v121
	v_mul_f32_e32 v83, v83, v85
	v_mul_f32_e32 v83, v83, v86
	v_cvt_pk_bf16_f32 v83, v84, v83
	v_mov_b64_e32 v[84:85], s[62:63]
	v_mad_i64_i32 v[84:85], s[34:35], v126, s87, v[84:85]
	v_lshl_add_u64 v[84:85], v[146:147], 2, v[84:85]
	global_store_dwordx4 v[84:85], v[80:83], off
.LBB0_867:
	s_or_b64 exec, exec, s[22:23]
	s_movk_i32 s6, 0x1fe0
	v_cmp_gt_i32_e64 s[52:53], s6, v196
	s_and_saveexec_b64 s[22:23], s[52:53]
	s_cbranch_execz .LBB0_885
	s_waitcnt vmcnt(2)
	v_add_f32_e32 v76, v76, v96
	v_mul_f32_e32 v76, 0xbfb8aa3b, v76
	v_exp_f32_e32 v76, v76
	s_nop 0
	v_add_f32_e32 v76, 1.0, v76
	v_rcp_f32_e32 v76, v76
	s_nop 0
	v_mul_f32_e32 v76, v92, v76
	v_add_f32_e32 v81, v76, v76
	v_cmp_nlt_f32_e64 s[54:55], s95, v81
	s_and_saveexec_b64 s[34:35], s[54:55]
	s_xor_b64 s[36:37], exec, s[34:35]
	v_mul_f32_e32 v80, 0x3fb8aa3b, v81
	v_exp_f32_e32 v80, v80
	s_nop 0
	v_sub_f32_e32 v80, 1.0, v80
	s_andn2_saveexec_b64 s[36:37], s[36:37]
	v_fma_f32 v80, v81, 0.5, 1.0
	v_mul_f32_e64 v80, v80, -v81
	s_or_b64 exec, exec, s[36:37]
	v_add_f32_e32 v72, v72, v88
	v_mul_f32_e32 v72, 0xbfb8aa3b, v72
	v_exp_f32_e32 v72, v72
	v_add_f32_e32 v77, v77, v97
	v_mul_f32_e32 v77, 0xbfb8aa3b, v77
	v_exp_f32_e32 v77, v77
	v_max_f32_e32 v80, v80, v80
	v_add_f32_e32 v72, 1.0, v72
	v_max_f32_e32 v80, 0, v80
	v_rcp_f32_e32 v72, v72
	v_sqrt_f32_e32 v80, v80
	v_add_f32_e32 v77, 1.0, v77
	v_rcp_f32_e32 v77, v77
	v_lshlrev_b32_e32 v81, 16, v118
	v_mul_f32_e32 v72, v72, v80
	v_mul_f32_e32 v72, v72, v81
	v_cvt_pk_bf16_f32 v72, v76, v72
	v_mul_f32_e32 v76, v93, v77
	v_add_f32_e32 v80, v76, v76
	v_cmp_nlt_f32_e64 s[54:55], s95, v80
	s_and_saveexec_b64 s[34:35], s[54:55]
	s_xor_b64 s[36:37], exec, s[34:35]
	v_mul_f32_e32 v77, 0x3fb8aa3b, v80
	v_exp_f32_e32 v77, v77
	s_nop 0
	v_sub_f32_e32 v77, 1.0, v77
	s_andn2_saveexec_b64 s[36:37], s[36:37]
	v_fma_f32 v77, v80, 0.5, 1.0
	v_mul_f32_e64 v77, v77, -v80
	s_or_b64 exec, exec, s[36:37]
; __device__ __forceinline__ unsigned cvt_pk_bf16(float lo, float hi) { unsigned r; asm volatile("v_cvt_pk_bf16_f32 %0, %1, %2" : "=v"(r) : "v"(lo), "v"(hi)); return r; }
; __device__ __forceinline__ float bflo(unsigned w) { return __uint_as_float(w << 16); }
; __device__ __forceinline__ float bfhi(unsigned w) { return __uint_as_float(w & 0xffff0000u); }
; __device__ __forceinline__ float fsigmoid(float x) { return __builtin_amdgcn_rcpf(1.0f + __expf(-x)); }
;     __device__ __forceinline__ void operator()(const f32x4 (&acc)[2][2][4][2], const Unit& u, int wr, int wc, int fr, int fq) const {
;     ...
;             for (int ai = 0; ai < 2; ++ai) { u32x2 xq[4];
; #pragma unroll
;                 for (int m = 0; m < 4; ++m) { const int row = row0 + ai * 128 + m * 16; xq[m] = *(const u32x2*)(XC + (size_t)(row < TT ? row : TT - 1) * DRNN + ch0 + 16 * n); }
; #pragma unroll
;                 for (int m = 0; m < 4; ++m) { const int row = row0 + ai * 128 + m * 16;
;                     if (row < TT) { const size_t off = (size_t)row * DRNN + ch0 + 16 * n; const u32x2 xw = xq[m]; const f32x4 xc = (f32x4){bflo(xw.x), bfhi(xw.x), bflo(xw.y), bfhi(xw.y)}; u32x4 o;
; #pragma unroll
;                         for (int i = 0; i < 4; ++i) { const float r = fsigmoid(acc[ai][0][m][n][i] + ba[i]), ig = fsigmoid(acc[ai][1][m][n][i] + bx[i]);
;                             const float la = r * lv[i], x2 = la + la, m = x2 > -1e-3f ? -x2 * fmaf(x2, 0.5f, 1.0f) : 1.0f - __expf(x2);
;                             o[i] = cvt_pk_bf16(la, __builtin_amdgcn_sqrtf(fmaxf(m, 0.0f)) * ig * xc[i]); }
;                         *(u32x4*)(AB + off) = o; } }
;                 asm volatile("" ::: "memory"); } }
	v_add_f32_e32 v73, v73, v89
	v_mul_f32_e32 v73, 0xbfb8aa3b, v73
	v_exp_f32_e32 v73, v73
	v_add_f32_e32 v78, v78, v98
	v_mul_f32_e32 v78, 0xbfb8aa3b, v78
	v_exp_f32_e32 v78, v78
	v_max_f32_e32 v77, v77, v77
	v_add_f32_e32 v73, 1.0, v73
	v_max_f32_e32 v77, 0, v77
	v_rcp_f32_e32 v73, v73
	v_sqrt_f32_e32 v77, v77
	v_add_f32_e32 v78, 1.0, v78
	v_rcp_f32_e32 v78, v78
	v_and_b32_e32 v80, 0xffff0000, v118
	v_mul_f32_e32 v73, v73, v77
	v_mul_f32_e32 v73, v73, v80
	v_cvt_pk_bf16_f32 v73, v76, v73
	v_mul_f32_e32 v76, v94, v78
	v_add_f32_e32 v78, v76, v76
	v_cmp_nlt_f32_e64 s[54:55], s95, v78
	s_and_saveexec_b64 s[34:35], s[54:55]
	s_xor_b64 s[36:37], exec, s[34:35]
	v_mul_f32_e32 v77, 0x3fb8aa3b, v78
	v_exp_f32_e32 v77, v77
	s_nop 0
	v_sub_f32_e32 v77, 1.0, v77
	s_andn2_saveexec_b64 s[36:37], s[36:37]
	v_fma_f32 v77, v78, 0.5, 1.0
	v_mul_f32_e64 v77, v77, -v78
	s_or_b64 exec, exec, s[36:37]
	v_add_f32_e32 v74, v74, v90
	v_mul_f32_e32 v74, 0xbfb8aa3b, v74
	v_exp_f32_e32 v74, v74
	v_add_f32_e32 v78, v79, v99
	v_mul_f32_e32 v78, 0xbfb8aa3b, v78
	v_exp_f32_e32 v78, v78
	v_max_f32_e32 v77, v77, v77
	v_add_f32_e32 v74, 1.0, v74
	v_max_f32_e32 v77, 0, v77
	v_rcp_f32_e32 v74, v74
	v_sqrt_f32_e32 v77, v77
	v_add_f32_e32 v78, 1.0, v78
	v_rcp_f32_e32 v78, v78
	v_lshlrev_b32_e32 v79, 16, v119
	v_mul_f32_e32 v74, v74, v77
	v_mul_f32_e32 v74, v74, v79
	v_cvt_pk_bf16_f32 v74, v76, v74
	v_mul_f32_e32 v76, v95, v78
	v_add_f32_e32 v78, v76, v76
	v_cmp_nlt_f32_e64 s[54:55], s95, v78
	s_and_saveexec_b64 s[34:35], s[54:55]
	s_xor_b64 s[36:37], exec, s[34:35]
	v_mul_f32_e32 v77, 0x3fb8aa3b, v78
	v_exp_f32_e32 v77, v77
	s_nop 0
	v_sub_f32_e32 v77, 1.0, v77
	s_andn2_saveexec_b64 s[36:37], s[36:37]
	v_fma_f32 v77, v78, 0.5, 1.0
	v_mul_f32_e64 v77, v77, -v78
	s_or_b64 exec, exec, s[36:37]
	v_add_f32_e32 v75, v75, v91
	v_mul_f32_e32 v75, 0xbfb8aa3b, v75
	v_exp_f32_e32 v75, v75
	v_max_f32_e32 v77, v77, v77
	v_max_f32_e32 v77, 0, v77
	v_sqrt_f32_e32 v77, v77
	v_add_f32_e32 v75, 1.0, v75
	v_rcp_f32_e32 v75, v75
	v_and_b32_e32 v78, 0xffff0000, v119
	v_mul_f32_e32 v75, v75, v77
	v_mul_f32_e32 v75, v75, v78
	v_cvt_pk_bf16_f32 v75, v76, v75
	v_mov_b64_e32 v[76:77], s[62:63]
	v_mad_i64_i32 v[76:77], s[34:35], v125, s87, v[76:77]
	v_lshl_add_u64 v[76:77], v[146:147], 2, v[76:77]
	global_store_dwordx4 v[76:77], v[72:75], off
.LBB0_885:
	s_or_b64 exec, exec, s[22:23]
	s_movk_i32 s6, 0x1fd0
	v_cmp_gt_i32_e64 s[54:55], s6, v196
	s_and_saveexec_b64 s[22:23], s[54:55]
	s_cbranch_execz .LBB0_903
	s_waitcnt vmcnt(3)
	v_add_f32_e32 v68, v68, v96
	v_mul_f32_e32 v68, 0xbfb8aa3b, v68
	v_exp_f32_e32 v68, v68
	s_nop 0
	v_add_f32_e32 v68, 1.0, v68
	v_rcp_f32_e32 v68, v68
	s_nop 0
	v_mul_f32_e32 v68, v92, v68
	v_add_f32_e32 v73, v68, v68
	v_cmp_nlt_f32_e64 s[56:57], s95, v73
	s_and_saveexec_b64 s[34:35], s[56:57]
	s_xor_b64 s[36:37], exec, s[34:35]
	v_mul_f32_e32 v72, 0x3fb8aa3b, v73
	v_exp_f32_e32 v72, v72
	s_nop 0
	v_sub_f32_e32 v72, 1.0, v72
	s_andn2_saveexec_b64 s[36:37], s[36:37]
	v_fma_f32 v72, v73, 0.5, 1.0
	v_mul_f32_e64 v72, v72, -v73
	s_or_b64 exec, exec, s[36:37]
	v_add_f32_e32 v64, v64, v88
	v_mul_f32_e32 v64, 0xbfb8aa3b, v64
	v_exp_f32_e32 v64, v64
	v_add_f32_e32 v69, v69, v97
	v_mul_f32_e32 v69, 0xbfb8aa3b, v69
	v_exp_f32_e32 v69, v69
	v_max_f32_e32 v72, v72, v72
	v_add_f32_e32 v64, 1.0, v64
	v_max_f32_e32 v72, 0, v72
	v_rcp_f32_e32 v64, v64
	v_sqrt_f32_e32 v72, v72
	v_add_f32_e32 v69, 1.0, v69
	v_rcp_f32_e32 v69, v69
	v_lshlrev_b32_e32 v73, 16, v116
	v_mul_f32_e32 v64, v64, v72
	v_mul_f32_e32 v64, v64, v73
	v_cvt_pk_bf16_f32 v64, v68, v64
	v_mul_f32_e32 v68, v93, v69
	v_add_f32_e32 v72, v68, v68
	v_cmp_nlt_f32_e64 s[56:57], s95, v72
	s_and_saveexec_b64 s[34:35], s[56:57]
	s_xor_b64 s[36:37], exec, s[34:35]
	v_mul_f32_e32 v69, 0x3fb8aa3b, v72
	v_exp_f32_e32 v69, v69
	s_nop 0
	v_sub_f32_e32 v69, 1.0, v69
	s_andn2_saveexec_b64 s[36:37], s[36:37]
	v_fma_f32 v69, v72, 0.5, 1.0
	v_mul_f32_e64 v69, v69, -v72
	s_or_b64 exec, exec, s[36:37]
	v_add_f32_e32 v65, v65, v89
	v_mul_f32_e32 v65, 0xbfb8aa3b, v65
	v_exp_f32_e32 v65, v65
	v_add_f32_e32 v70, v70, v98
	v_mul_f32_e32 v70, 0xbfb8aa3b, v70
	v_exp_f32_e32 v70, v70
	v_max_f32_e32 v69, v69, v69
	v_add_f32_e32 v65, 1.0, v65
	v_max_f32_e32 v69, 0, v69
	v_rcp_f32_e32 v65, v65
	v_sqrt_f32_e32 v69, v69
	v_add_f32_e32 v70, 1.0, v70
	v_rcp_f32_e32 v70, v70
	v_and_b32_e32 v72, 0xffff0000, v116
	v_mul_f32_e32 v65, v65, v69
	v_mul_f32_e32 v65, v65, v72
	v_cvt_pk_bf16_f32 v65, v68, v65
	v_mul_f32_e32 v68, v94, v70
	v_add_f32_e32 v70, v68, v68
	v_cmp_nlt_f32_e64 s[56:57], s95, v70
	s_and_saveexec_b64 s[34:35], s[56:57]
	s_xor_b64 s[36:37], exec, s[34:35]
	v_mul_f32_e32 v69, 0x3fb8aa3b, v70
	v_exp_f32_e32 v69, v69
	s_nop 0
	v_sub_f32_e32 v69, 1.0, v69
	s_andn2_saveexec_b64 s[36:37], s[36:37]
	v_fma_f32 v69, v70, 0.5, 1.0
	v_mul_f32_e64 v69, v69, -v70
	s_or_b64 exec, exec, s[36:37]
	v_add_f32_e32 v66, v66, v90
	v_mul_f32_e32 v66, 0xbfb8aa3b, v66
	v_exp_f32_e32 v66, v66
	v_add_f32_e32 v70, v71, v99
	v_mul_f32_e32 v70, 0xbfb8aa3b, v70
	v_exp_f32_e32 v70, v70
	v_max_f32_e32 v69, v69, v69
	v_add_f32_e32 v66, 1.0, v66
	v_max_f32_e32 v69, 0, v69
	v_rcp_f32_e32 v66, v66
	v_sqrt_f32_e32 v69, v69
	v_add_f32_e32 v70, 1.0, v70
	v_rcp_f32_e32 v70, v70
	v_lshlrev_b32_e32 v71, 16, v117
	v_mul_f32_e32 v66, v66, v69
	v_mul_f32_e32 v66, v66, v71
	v_cvt_pk_bf16_f32 v66, v68, v66
	v_mul_f32_e32 v68, v95, v70
	v_add_f32_e32 v70, v68, v68
	v_cmp_nlt_f32_e64 s[56:57], s95, v70
	s_and_saveexec_b64 s[34:35], s[56:57]
	s_xor_b64 s[36:37], exec, s[34:35]
	v_mul_f32_e32 v69, 0x3fb8aa3b, v70
	v_exp_f32_e32 v69, v69
	s_nop 0
	v_sub_f32_e32 v69, 1.0, v69
	s_andn2_saveexec_b64 s[36:37], s[36:37]
	v_fma_f32 v69, v70, 0.5, 1.0
	v_mul_f32_e64 v69, v69, -v70
	s_or_b64 exec, exec, s[36:37]
	v_add_f32_e32 v67, v67, v91
	v_mul_f32_e32 v67, 0xbfb8aa3b, v67
	v_exp_f32_e32 v67, v67
	v_max_f32_e32 v69, v69, v69
	v_max_f32_e32 v69, 0, v69
	v_sqrt_f32_e32 v69, v69
	v_add_f32_e32 v67, 1.0, v67
	v_rcp_f32_e32 v67, v67
	v_and_b32_e32 v70, 0xffff0000, v117
	v_mul_f32_e32 v67, v67, v69
	v_mul_f32_e32 v67, v67, v70
	v_cvt_pk_bf16_f32 v67, v68, v67
	v_mov_b64_e32 v[68:69], s[62:63]
	v_mad_i64_i32 v[68:69], s[34:35], v124, s87, v[68:69]
	v_lshl_add_u64 v[68:69], v[146:147], 2, v[68:69]
	global_store_dwordx4 v[68:69], v[64:67], off

; __device__ __forceinline__ unsigned cvt_pk_bf16(float lo, float hi) { unsigned r; asm volatile("v_cvt_pk_bf16_f32 %0, %1, %2" : "=v"(r) : "v"(lo), "v"(hi)); return r; }
; __device__ __forceinline__ float bflo(unsigned w) { return __uint_as_float(w << 16); }
; __device__ __forceinline__ float bfhi(unsigned w) { return __uint_as_float(w & 0xffff0000u); }
; __device__ __forceinline__ float fsigmoid(float x) { return __builtin_amdgcn_rcpf(1.0f + __expf(-x)); }
;     __device__ __forceinline__ void operator()(const f32x4 (&acc)[2][2][4][2], const Unit& u, int wr, int wc, int fr, int fq) const {
;     ...
;             for (int ai = 0; ai < 2; ++ai) { u32x2 xq[4];
; #pragma unroll
;                 for (int m = 0; m < 4; ++m) { const int row = row0 + ai * 128 + m * 16; xq[m] = *(const u32x2*)(XC + (size_t)(row < TT ? row : TT - 1) * DRNN + ch0 + 16 * n); }
; #pragma unroll
;                 for (int m = 0; m < 4; ++m) { const int row = row0 + ai * 128 + m * 16;
;                     if (row < TT) { const size_t off = (size_t)row * DRNN + ch0 + 16 * n; const u32x2 xw = xq[m]; const f32x4 xc = (f32x4){bflo(xw.x), bfhi(xw.x), bflo(xw.y), bfhi(xw.y)}; u32x4 o;
; #pragma unroll
;                         for (int i = 0; i < 4; ++i) { const float r = fsigmoid(acc[ai][0][m][n][i] + ba[i]), ig = fsigmoid(acc[ai][1][m][n][i] + bx[i]);
;                             const float la = r * lv[i], x2 = la + la, m = x2 > -1e-3f ? -x2 * fmaf(x2, 0.5f, 1.0f) : 1.0f - __expf(x2);
;                             o[i] = cvt_pk_bf16(la, __builtin_amdgcn_sqrtf(fmaxf(m, 0.0f)) * ig * xc[i]); }
;                         *(u32x4*)(AB + off) = o; } }
;                 asm volatile("" ::: "memory"); } }
.LBB0_923:
	s_waitcnt vmcnt(1)
	v_add_f32_e32 v52, v52, v72
	v_mul_f32_e32 v52, 0xbfb8aa3b, v52
	v_exp_f32_e32 v52, v52
	s_nop 0
	v_add_f32_e32 v52, 1.0, v52
	v_rcp_f32_e32 v52, v52
	s_nop 0
	v_mul_f32_e32 v52, v68, v52
	v_add_f32_e32 v57, v52, v52
	v_cmp_nlt_f32_e32 vcc, s95, v57
	s_and_saveexec_b64 s[34:35], vcc
	s_xor_b64 s[36:37], exec, s[34:35]
	v_mul_f32_e32 v56, 0x3fb8aa3b, v57
	v_exp_f32_e32 v56, v56
	s_nop 0
	v_sub_f32_e32 v56, 1.0, v56
	s_andn2_saveexec_b64 s[36:37], s[36:37]
	v_fma_f32 v56, v57, 0.5, 1.0
	v_mul_f32_e64 v56, v56, -v57
	s_or_b64 exec, exec, s[36:37]
	v_add_f32_e32 v48, v48, v64
	v_mul_f32_e32 v48, 0xbfb8aa3b, v48
	v_exp_f32_e32 v48, v48
	v_add_f32_e32 v53, v53, v73
	v_mul_f32_e32 v53, 0xbfb8aa3b, v53
	v_exp_f32_e32 v53, v53
	v_max_f32_e32 v56, v56, v56
	v_add_f32_e32 v48, 1.0, v48
	v_max_f32_e32 v56, 0, v56
	v_rcp_f32_e32 v48, v48
	v_sqrt_f32_e32 v56, v56
	v_add_f32_e32 v53, 1.0, v53
	v_rcp_f32_e32 v53, v53
	v_lshlrev_b32_e32 v57, 16, v80
	v_mul_f32_e32 v48, v48, v56
	v_mul_f32_e32 v48, v48, v57
	v_cvt_pk_bf16_f32 v48, v52, v48
	v_mul_f32_e32 v52, v69, v53
	v_add_f32_e32 v56, v52, v52
	v_cmp_nlt_f32_e32 vcc, s95, v56
	s_and_saveexec_b64 s[34:35], vcc
	s_xor_b64 s[36:37], exec, s[34:35]
	v_mul_f32_e32 v53, 0x3fb8aa3b, v56
	v_exp_f32_e32 v53, v53
	s_nop 0
	v_sub_f32_e32 v53, 1.0, v53
	s_andn2_saveexec_b64 s[36:37], s[36:37]
	v_fma_f32 v53, v56, 0.5, 1.0
	v_mul_f32_e64 v53, v53, -v56
	s_or_b64 exec, exec, s[36:37]
	v_add_f32_e32 v49, v49, v65
	v_mul_f32_e32 v49, 0xbfb8aa3b, v49
	v_exp_f32_e32 v49, v49
	v_add_f32_e32 v54, v54, v74
	v_mul_f32_e32 v54, 0xbfb8aa3b, v54
	v_exp_f32_e32 v54, v54
	v_max_f32_e32 v53, v53, v53
	v_add_f32_e32 v49, 1.0, v49
	v_max_f32_e32 v53, 0, v53
	v_rcp_f32_e32 v49, v49
	v_sqrt_f32_e32 v53, v53
	v_add_f32_e32 v54, 1.0, v54
	v_rcp_f32_e32 v54, v54
	v_and_b32_e32 v56, 0xffff0000, v80
	v_mul_f32_e32 v49, v49, v53
	v_mul_f32_e32 v49, v49, v56
	v_cvt_pk_bf16_f32 v49, v52, v49
	v_mul_f32_e32 v52, v70, v54
	v_add_f32_e32 v54, v52, v52
	v_cmp_nlt_f32_e32 vcc, s95, v54
	s_and_saveexec_b64 s[34:35], vcc
	s_xor_b64 s[36:37], exec, s[34:35]
	v_mul_f32_e32 v53, 0x3fb8aa3b, v54
	v_exp_f32_e32 v53, v53
	s_nop 0
	v_sub_f32_e32 v53, 1.0, v53
	s_andn2_saveexec_b64 s[36:37], s[36:37]
	v_fma_f32 v53, v54, 0.5, 1.0
	v_mul_f32_e64 v53, v53, -v54
	s_or_b64 exec, exec, s[36:37]
	v_add_f32_e32 v50, v50, v66
	v_mul_f32_e32 v50, 0xbfb8aa3b, v50
	v_exp_f32_e32 v50, v50
	v_add_f32_e32 v54, v55, v75
	v_mul_f32_e32 v54, 0xbfb8aa3b, v54
	v_exp_f32_e32 v54, v54
	v_max_f32_e32 v53, v53, v53
	v_add_f32_e32 v50, 1.0, v50
	v_max_f32_e32 v53, 0, v53
	v_rcp_f32_e32 v50, v50
	v_sqrt_f32_e32 v53, v53
	v_add_f32_e32 v54, 1.0, v54
	v_rcp_f32_e32 v54, v54
	v_lshlrev_b32_e32 v55, 16, v81
	v_mul_f32_e32 v50, v50, v53
	v_mul_f32_e32 v50, v50, v55
	v_cvt_pk_bf16_f32 v50, v52, v50
	v_mul_f32_e32 v52, v71, v54
	v_add_f32_e32 v54, v52, v52
	v_cmp_nlt_f32_e32 vcc, s95, v54
	s_and_saveexec_b64 s[34:35], vcc
	s_xor_b64 s[36:37], exec, s[34:35]
	v_mul_f32_e32 v53, 0x3fb8aa3b, v54
	v_exp_f32_e32 v53, v53
	s_nop 0
	v_sub_f32_e32 v53, 1.0, v53
	s_andn2_saveexec_b64 s[36:37], s[36:37]
	v_fma_f32 v53, v54, 0.5, 1.0
	v_mul_f32_e64 v53, v53, -v54
	s_or_b64 exec, exec, s[36:37]
	v_add_f32_e32 v51, v51, v67
	v_mul_f32_e32 v51, 0xbfb8aa3b, v51
	v_exp_f32_e32 v51, v51
	v_max_f32_e32 v53, v53, v53
	v_max_f32_e32 v53, 0, v53
	v_sqrt_f32_e32 v53, v53
	v_add_f32_e32 v51, 1.0, v51
	v_rcp_f32_e32 v51, v51
	v_and_b32_e32 v54, 0xffff0000, v81
	v_mul_f32_e32 v51, v51, v53
	v_mul_f32_e32 v51, v51, v54
	v_cvt_pk_bf16_f32 v51, v52, v51
	v_mov_b64_e32 v[52:53], s[62:63]
	v_mad_i64_i32 v[52:53], s[34:35], v195, s87, v[52:53]
	v_lshl_add_u64 v[52:53], v[146:147], 2, v[52:53]
	global_store_dwordx4 v[52:53], v[48:51], off offset:64
	s_or_b64 exec, exec, s[22:23]
	s_and_saveexec_b64 s[22:23], s[44:45]
	s_cbranch_execz .LBB0_957
.LBB0_940:
	s_waitcnt vmcnt(2)
	v_add_f32_e32 v44, v44, v72
	v_mul_f32_e32 v44, 0xbfb8aa3b, v44
	v_exp_f32_e32 v44, v44
	s_nop 0
	v_add_f32_e32 v44, 1.0, v44
	v_rcp_f32_e32 v44, v44
	s_nop 0
	v_mul_f32_e32 v44, v68, v44
	v_add_f32_e32 v49, v44, v44
	v_cmp_nlt_f32_e32 vcc, s95, v49
	s_and_saveexec_b64 s[34:35], vcc
	s_xor_b64 s[36:37], exec, s[34:35]
	v_mul_f32_e32 v48, 0x3fb8aa3b, v49
	v_exp_f32_e32 v48, v48
	s_nop 0
	v_sub_f32_e32 v48, 1.0, v48
	s_andn2_saveexec_b64 s[36:37], s[36:37]
	v_fma_f32 v48, v49, 0.5, 1.0
	v_mul_f32_e64 v48, v48, -v49
	s_or_b64 exec, exec, s[36:37]
	v_add_f32_e32 v40, v40, v64
	v_mul_f32_e32 v40, 0xbfb8aa3b, v40
	v_exp_f32_e32 v40, v40
	v_add_f32_e32 v45, v45, v73
	v_mul_f32_e32 v45, 0xbfb8aa3b, v45
	v_exp_f32_e32 v45, v45
	v_max_f32_e32 v48, v48, v48
	v_add_f32_e32 v40, 1.0, v40
	v_max_f32_e32 v48, 0, v48
	v_rcp_f32_e32 v40, v40
	v_sqrt_f32_e32 v48, v48
	v_add_f32_e32 v45, 1.0, v45
	v_rcp_f32_e32 v45, v45
	v_lshlrev_b32_e32 v49, 16, v78
	v_mul_f32_e32 v40, v40, v48
	v_mul_f32_e32 v40, v40, v49
	v_cvt_pk_bf16_f32 v40, v44, v40
	v_mul_f32_e32 v44, v69, v45
	v_add_f32_e32 v48, v44, v44
	v_cmp_nlt_f32_e32 vcc, s95, v48
	s_and_saveexec_b64 s[34:35], vcc
	s_xor_b64 s[36:37], exec, s[34:35]
	v_mul_f32_e32 v45, 0x3fb8aa3b, v48
	v_exp_f32_e32 v45, v45
	s_nop 0
	v_sub_f32_e32 v45, 1.0, v45
	s_andn2_saveexec_b64 s[36:37], s[36:37]
	v_fma_f32 v45, v48, 0.5, 1.0
	v_mul_f32_e64 v45, v45, -v48
	s_or_b64 exec, exec, s[36:37]
	v_add_f32_e32 v41, v41, v65
	v_mul_f32_e32 v41, 0xbfb8aa3b, v41
	v_exp_f32_e32 v41, v41
	v_add_f32_e32 v46, v46, v74
	v_mul_f32_e32 v46, 0xbfb8aa3b, v46
	v_exp_f32_e32 v46, v46
	v_max_f32_e32 v45, v45, v45
	v_add_f32_e32 v41, 1.0, v41
	v_max_f32_e32 v45, 0, v45
	v_rcp_f32_e32 v41, v41
	v_sqrt_f32_e32 v45, v45
; __device__ __forceinline__ unsigned cvt_pk_bf16(float lo, float hi) { unsigned r; asm volatile("v_cvt_pk_bf16_f32 %0, %1, %2" : "=v"(r) : "v"(lo), "v"(hi)); return r; }
; __device__ __forceinline__ float bflo(unsigned w) { return __uint_as_float(w << 16); }
; __device__ __forceinline__ float bfhi(unsigned w) { return __uint_as_float(w & 0xffff0000u); }
; __device__ __forceinline__ float fsigmoid(float x) { return __builtin_amdgcn_rcpf(1.0f + __expf(-x)); }
;     __device__ __forceinline__ void operator()(const f32x4 (&acc)[2][2][4][2], const Unit& u, int wr, int wc, int fr, int fq) const {
;     ...
;             for (int ai = 0; ai < 2; ++ai) { u32x2 xq[4];
; #pragma unroll
;                 for (int m = 0; m < 4; ++m) { const int row = row0 + ai * 128 + m * 16; xq[m] = *(const u32x2*)(XC + (size_t)(row < TT ? row : TT - 1) * DRNN + ch0 + 16 * n); }
; #pragma unroll
;                 for (int m = 0; m < 4; ++m) { const int row = row0 + ai * 128 + m * 16;
;                     if (row < TT) { const size_t off = (size_t)row * DRNN + ch0 + 16 * n; const u32x2 xw = xq[m]; const f32x4 xc = (f32x4){bflo(xw.x), bfhi(xw.x), bflo(xw.y), bfhi(xw.y)}; u32x4 o;
; #pragma unroll
;                         for (int i = 0; i < 4; ++i) { const float r = fsigmoid(acc[ai][0][m][n][i] + ba[i]), ig = fsigmoid(acc[ai][1][m][n][i] + bx[i]);
;                             const float la = r * lv[i], x2 = la + la, m = x2 > -1e-3f ? -x2 * fmaf(x2, 0.5f, 1.0f) : 1.0f - __expf(x2);
;                             o[i] = cvt_pk_bf16(la, __builtin_amdgcn_sqrtf(fmaxf(m, 0.0f)) * ig * xc[i]); }
;                         *(u32x4*)(AB + off) = o; } }
;                 asm volatile("" ::: "memory"); } }
	v_add_f32_e32 v46, 1.0, v46
	v_rcp_f32_e32 v46, v46
	v_and_b32_e32 v48, 0xffff0000, v78
	v_mul_f32_e32 v41, v41, v45
	v_mul_f32_e32 v41, v41, v48
	v_cvt_pk_bf16_f32 v41, v44, v41
	v_mul_f32_e32 v44, v70, v46
	v_add_f32_e32 v46, v44, v44
	v_cmp_nlt_f32_e32 vcc, s95, v46
	s_and_saveexec_b64 s[34:35], vcc
	s_xor_b64 s[36:37], exec, s[34:35]
	v_mul_f32_e32 v45, 0x3fb8aa3b, v46
	v_exp_f32_e32 v45, v45
	s_nop 0
	v_sub_f32_e32 v45, 1.0, v45
	s_andn2_saveexec_b64 s[36:37], s[36:37]
	v_fma_f32 v45, v46, 0.5, 1.0
	v_mul_f32_e64 v45, v45, -v46
	s_or_b64 exec, exec, s[36:37]
	v_add_f32_e32 v42, v42, v66
	v_mul_f32_e32 v42, 0xbfb8aa3b, v42
	v_exp_f32_e32 v42, v42
	v_add_f32_e32 v46, v47, v75
	v_mul_f32_e32 v46, 0xbfb8aa3b, v46
	v_exp_f32_e32 v46, v46
	v_max_f32_e32 v45, v45, v45
	v_add_f32_e32 v42, 1.0, v42
	v_max_f32_e32 v45, 0, v45
	v_rcp_f32_e32 v42, v42
	v_sqrt_f32_e32 v45, v45
	v_add_f32_e32 v46, 1.0, v46
	v_rcp_f32_e32 v46, v46
	v_lshlrev_b32_e32 v47, 16, v79
	v_mul_f32_e32 v42, v42, v45
	v_mul_f32_e32 v42, v42, v47
	v_cvt_pk_bf16_f32 v42, v44, v42
	v_mul_f32_e32 v44, v71, v46
	v_add_f32_e32 v46, v44, v44
	v_cmp_nlt_f32_e32 vcc, s95, v46
	s_and_saveexec_b64 s[34:35], vcc
	s_xor_b64 s[36:37], exec, s[34:35]
	v_mul_f32_e32 v45, 0x3fb8aa3b, v46
	v_exp_f32_e32 v45, v45
	s_nop 0
	v_sub_f32_e32 v45, 1.0, v45
	s_andn2_saveexec_b64 s[36:37], s[36:37]
	v_fma_f32 v45, v46, 0.5, 1.0
	v_mul_f32_e64 v45, v45, -v46
	s_or_b64 exec, exec, s[36:37]
	v_add_f32_e32 v43, v43, v67
	v_mul_f32_e32 v43, 0xbfb8aa3b, v43
	v_exp_f32_e32 v43, v43
	v_max_f32_e32 v45, v45, v45
	v_max_f32_e32 v45, 0, v45
	v_sqrt_f32_e32 v45, v45
	v_add_f32_e32 v43, 1.0, v43
	v_rcp_f32_e32 v43, v43
	v_and_b32_e32 v46, 0xffff0000, v79
	v_mul_f32_e32 v43, v43, v45
	v_mul_f32_e32 v43, v43, v46
	v_cvt_pk_bf16_f32 v43, v44, v43
	v_mov_b64_e32 v[44:45], s[62:63]
	v_mad_i64_i32 v[44:45], s[34:35], v194, s87, v[44:45]
	v_lshl_add_u64 v[44:45], v[146:147], 2, v[44:45]
	global_store_dwordx4 v[44:45], v[40:43], off offset:64
.LBB0_957:
	s_or_b64 exec, exec, s[22:23]
	s_and_saveexec_b64 s[22:23], s[46:47]
	s_mov_b32 s33, 0xa000
	s_mov_b32 s46, 0x11000
	s_cbranch_execz .LBB0_975
	s_waitcnt vmcnt(3)
	v_add_f32_e32 v36, v36, v72
	v_mul_f32_e32 v36, 0xbfb8aa3b, v36
	v_exp_f32_e32 v36, v36
	s_nop 0
	v_add_f32_e32 v36, 1.0, v36
	v_rcp_f32_e32 v36, v36
	s_nop 0
	v_mul_f32_e32 v36, v68, v36
	v_add_f32_e32 v41, v36, v36
	v_cmp_nlt_f32_e32 vcc, s95, v41
	s_and_saveexec_b64 s[34:35], vcc
	s_xor_b64 s[36:37], exec, s[34:35]
	v_mul_f32_e32 v40, 0x3fb8aa3b, v41
	v_exp_f32_e32 v40, v40
	s_nop 0
	v_sub_f32_e32 v40, 1.0, v40
	s_andn2_saveexec_b64 s[36:37], s[36:37]
	v_fma_f32 v40, v41, 0.5, 1.0
	v_mul_f32_e64 v40, v40, -v41
	s_or_b64 exec, exec, s[36:37]
	v_add_f32_e32 v32, v32, v64
	v_mul_f32_e32 v32, 0xbfb8aa3b, v32
	v_exp_f32_e32 v32, v32
	v_add_f32_e32 v37, v37, v73
	v_mul_f32_e32 v37, 0xbfb8aa3b, v37
	v_exp_f32_e32 v37, v37
	v_max_f32_e32 v40, v40, v40
	v_add_f32_e32 v32, 1.0, v32
	v_max_f32_e32 v40, 0, v40
	v_rcp_f32_e32 v32, v32
	v_sqrt_f32_e32 v40, v40
	v_add_f32_e32 v37, 1.0, v37
	v_rcp_f32_e32 v37, v37
	v_lshlrev_b32_e32 v41, 16, v76
	v_mul_f32_e32 v32, v32, v40
	v_mul_f32_e32 v32, v32, v41
	v_cvt_pk_bf16_f32 v32, v36, v32
	v_mul_f32_e32 v36, v69, v37
	v_add_f32_e32 v40, v36, v36
	v_cmp_nlt_f32_e32 vcc, s95, v40
	s_and_saveexec_b64 s[34:35], vcc
	s_xor_b64 s[36:37], exec, s[34:35]
	v_mul_f32_e32 v37, 0x3fb8aa3b, v40
	v_exp_f32_e32 v37, v37
	s_nop 0
	v_sub_f32_e32 v37, 1.0, v37
	s_andn2_saveexec_b64 s[36:37], s[36:37]
	v_fma_f32 v37, v40, 0.5, 1.0
	v_mul_f32_e64 v37, v37, -v40
	s_or_b64 exec, exec, s[36:37]
	v_add_f32_e32 v33, v33, v65
	v_mul_f32_e32 v33, 0xbfb8aa3b, v33
	v_exp_f32_e32 v33, v33
	v_add_f32_e32 v38, v38, v74
	v_mul_f32_e32 v38, 0xbfb8aa3b, v38
	v_exp_f32_e32 v38, v38
	v_max_f32_e32 v37, v37, v37
	v_add_f32_e32 v33, 1.0, v33
	v_max_f32_e32 v37, 0, v37
	v_rcp_f32_e32 v33, v33
	v_sqrt_f32_e32 v37, v37
	v_add_f32_e32 v38, 1.0, v38
	v_rcp_f32_e32 v38, v38
	v_and_b32_e32 v40, 0xffff0000, v76
	v_mul_f32_e32 v33, v33, v37
	v_mul_f32_e32 v33, v33, v40
	v_cvt_pk_bf16_f32 v33, v36, v33
	v_mul_f32_e32 v36, v70, v38
	v_add_f32_e32 v38, v36, v36
	v_cmp_nlt_f32_e32 vcc, s95, v38
	s_and_saveexec_b64 s[34:35], vcc
	s_xor_b64 s[36:37], exec, s[34:35]
	v_mul_f32_e32 v37, 0x3fb8aa3b, v38
	v_exp_f32_e32 v37, v37
	s_nop 0
	v_sub_f32_e32 v37, 1.0, v37
	s_andn2_saveexec_b64 s[36:37], s[36:37]
	v_fma_f32 v37, v38, 0.5, 1.0
	v_mul_f32_e64 v37, v37, -v38
	s_or_b64 exec, exec, s[36:37]
	v_add_f32_e32 v34, v34, v66
	v_mul_f32_e32 v34, 0xbfb8aa3b, v34
	v_exp_f32_e32 v34, v34
	v_add_f32_e32 v38, v39, v75
	v_mul_f32_e32 v38, 0xbfb8aa3b, v38
	v_exp_f32_e32 v38, v38
	v_max_f32_e32 v37, v37, v37
	v_add_f32_e32 v34, 1.0, v34
	v_max_f32_e32 v37, 0, v37
	v_rcp_f32_e32 v34, v34
	v_sqrt_f32_e32 v37, v37
	v_add_f32_e32 v38, 1.0, v38
	v_rcp_f32_e32 v38, v38
	v_lshlrev_b32_e32 v39, 16, v77
	v_mul_f32_e32 v34, v34, v37
	v_mul_f32_e32 v34, v34, v39
	v_cvt_pk_bf16_f32 v34, v36, v34
	v_mul_f32_e32 v36, v71, v38
	v_add_f32_e32 v38, v36, v36
	v_cmp_nlt_f32_e32 vcc, s95, v38
	s_and_saveexec_b64 s[34:35], vcc
	s_xor_b64 s[36:37], exec, s[34:35]
	v_mul_f32_e32 v37, 0x3fb8aa3b, v38
	v_exp_f32_e32 v37, v37
	s_nop 0
	v_sub_f32_e32 v37, 1.0, v37
	s_andn2_saveexec_b64 s[36:37], s[36:37]
	v_fma_f32 v37, v38, 0.5, 1.0
	v_mul_f32_e64 v37, v37, -v38
	s_or_b64 exec, exec, s[36:37]
	v_add_f32_e32 v35, v35, v67
	v_mul_f32_e32 v35, 0xbfb8aa3b, v35
	v_exp_f32_e32 v35, v35
	v_max_f32_e32 v37, v37, v37
	v_max_f32_e32 v37, 0, v37
	v_sqrt_f32_e32 v37, v37
	v_add_f32_e32 v35, 1.0, v35
	v_rcp_f32_e32 v35, v35
	v_and_b32_e32 v38, 0xffff0000, v77
	v_mul_f32_e32 v35, v35, v37
	v_mul_f32_e32 v35, v35, v38
	v_cvt_pk_bf16_f32 v35, v36, v35
	v_mov_b64_e32 v[36:37], s[62:63]
	v_mad_i64_i32 v[36:37], s[34:35], v193, s87, v[36:37]
	v_lshl_add_u64 v[36:37], v[146:147], 2, v[36:37]
	global_store_dwordx4 v[36:37], v[32:35], off offset:64

; __device__ __forceinline__ unsigned cvt_pk_bf16(float lo, float hi) { unsigned r; asm volatile("v_cvt_pk_bf16_f32 %0, %1, %2" : "=v"(r) : "v"(lo), "v"(hi)); return r; }
; __device__ __forceinline__ float bflo(unsigned w) { return __uint_as_float(w << 16); }
; __device__ __forceinline__ float bfhi(unsigned w) { return __uint_as_float(w & 0xffff0000u); }
; __device__ __forceinline__ float fsigmoid(float x) { return __builtin_amdgcn_rcpf(1.0f + __expf(-x)); }
;     __device__ __forceinline__ void operator()(const f32x4 (&acc)[2][2][4][2], const Unit& u, int wr, int wc, int fr, int fq) const {
;     ...
;             for (int ai = 0; ai < 2; ++ai) { u32x2 xq[4];
; #pragma unroll
;                 for (int m = 0; m < 4; ++m) { const int row = row0 + ai * 128 + m * 16; xq[m] = *(const u32x2*)(XC + (size_t)(row < TT ? row : TT - 1) * DRNN + ch0 + 16 * n); }
; #pragma unroll
;                 for (int m = 0; m < 4; ++m) { const int row = row0 + ai * 128 + m * 16;
;                     if (row < TT) { const size_t off = (size_t)row * DRNN + ch0 + 16 * n; const u32x2 xw = xq[m]; const f32x4 xc = (f32x4){bflo(xw.x), bfhi(xw.x), bflo(xw.y), bfhi(xw.y)}; u32x4 o;
; #pragma unroll
;                         for (int i = 0; i < 4; ++i) { const float r = fsigmoid(acc[ai][0][m][n][i] + ba[i]), ig = fsigmoid(acc[ai][1][m][n][i] + bx[i]);
;                             const float la = r * lv[i], x2 = la + la, m = x2 > -1e-3f ? -x2 * fmaf(x2, 0.5f, 1.0f) : 1.0f - __expf(x2);
;                             o[i] = cvt_pk_bf16(la, __builtin_amdgcn_sqrtf(fmaxf(m, 0.0f)) * ig * xc[i]); }
;                         *(u32x4*)(AB + off) = o; } }
;                 asm volatile("" ::: "memory"); } }
.LBB0_996:
	s_waitcnt vmcnt(1)
	v_add_f32_e32 v20, v20, v72
	v_mul_f32_e32 v20, 0xbfb8aa3b, v20
	v_exp_f32_e32 v20, v20
	s_nop 0
	v_add_f32_e32 v20, 1.0, v20
	v_rcp_f32_e32 v20, v20
	s_nop 0
	v_mul_f32_e32 v20, v68, v20
	v_add_f32_e32 v25, v20, v20
	v_cmp_nlt_f32_e32 vcc, s95, v25
	s_and_saveexec_b64 s[34:35], vcc
	s_xor_b64 s[36:37], exec, s[34:35]
	v_mul_f32_e32 v24, 0x3fb8aa3b, v25
	v_exp_f32_e32 v24, v24
	s_nop 0
	v_sub_f32_e32 v24, 1.0, v24
	s_andn2_saveexec_b64 s[36:37], s[36:37]
	v_fma_f32 v24, v25, 0.5, 1.0
	v_mul_f32_e64 v24, v24, -v25
	s_or_b64 exec, exec, s[36:37]
	v_add_f32_e32 v16, v16, v64
	v_mul_f32_e32 v16, 0xbfb8aa3b, v16
	v_exp_f32_e32 v16, v16
	v_add_f32_e32 v21, v21, v73
	v_mul_f32_e32 v21, 0xbfb8aa3b, v21
	v_exp_f32_e32 v21, v21
	v_max_f32_e32 v24, v24, v24
	v_add_f32_e32 v16, 1.0, v16
	v_max_f32_e32 v24, 0, v24
	v_rcp_f32_e32 v16, v16
	v_sqrt_f32_e32 v24, v24
	v_add_f32_e32 v21, 1.0, v21
	v_rcp_f32_e32 v21, v21
	v_lshlrev_b32_e32 v25, 16, v36
	v_mul_f32_e32 v16, v16, v24
	v_mul_f32_e32 v16, v16, v25
	v_cvt_pk_bf16_f32 v16, v20, v16
	v_mul_f32_e32 v20, v69, v21
	v_add_f32_e32 v24, v20, v20
	v_cmp_nlt_f32_e32 vcc, s95, v24
	s_and_saveexec_b64 s[34:35], vcc
	s_xor_b64 s[36:37], exec, s[34:35]
	v_mul_f32_e32 v21, 0x3fb8aa3b, v24
	v_exp_f32_e32 v21, v21
	s_nop 0
	v_sub_f32_e32 v21, 1.0, v21
	s_andn2_saveexec_b64 s[36:37], s[36:37]
	v_fma_f32 v21, v24, 0.5, 1.0
	v_mul_f32_e64 v21, v21, -v24
	s_or_b64 exec, exec, s[36:37]
	v_add_f32_e32 v17, v17, v65
	v_mul_f32_e32 v17, 0xbfb8aa3b, v17
	v_exp_f32_e32 v17, v17
	v_add_f32_e32 v22, v22, v74
	v_mul_f32_e32 v22, 0xbfb8aa3b, v22
	v_exp_f32_e32 v22, v22
	v_max_f32_e32 v21, v21, v21
	v_add_f32_e32 v17, 1.0, v17
	v_max_f32_e32 v21, 0, v21
	v_rcp_f32_e32 v17, v17
	v_sqrt_f32_e32 v21, v21
	v_add_f32_e32 v22, 1.0, v22
	v_rcp_f32_e32 v22, v22
	v_and_b32_e32 v24, 0xffff0000, v36
	v_mul_f32_e32 v17, v17, v21
	v_mul_f32_e32 v17, v17, v24
	v_cvt_pk_bf16_f32 v17, v20, v17
	v_mul_f32_e32 v20, v70, v22
	v_add_f32_e32 v22, v20, v20
	v_cmp_nlt_f32_e32 vcc, s95, v22
	s_and_saveexec_b64 s[34:35], vcc
	s_xor_b64 s[36:37], exec, s[34:35]
	v_mul_f32_e32 v21, 0x3fb8aa3b, v22
	v_exp_f32_e32 v21, v21
	s_nop 0
	v_sub_f32_e32 v21, 1.0, v21
	s_andn2_saveexec_b64 s[36:37], s[36:37]
	v_fma_f32 v21, v22, 0.5, 1.0
	v_mul_f32_e64 v21, v21, -v22
	s_or_b64 exec, exec, s[36:37]
	v_add_f32_e32 v18, v18, v66
	v_mul_f32_e32 v18, 0xbfb8aa3b, v18
	v_exp_f32_e32 v18, v18
	v_add_f32_e32 v22, v23, v75
	v_mul_f32_e32 v22, 0xbfb8aa3b, v22
	v_exp_f32_e32 v22, v22
	v_max_f32_e32 v21, v21, v21
	v_add_f32_e32 v18, 1.0, v18
	v_max_f32_e32 v21, 0, v21
	v_rcp_f32_e32 v18, v18
	v_sqrt_f32_e32 v21, v21
	v_add_f32_e32 v22, 1.0, v22
	v_rcp_f32_e32 v22, v22
	v_lshlrev_b32_e32 v23, 16, v37
	v_mul_f32_e32 v18, v18, v21
	v_mul_f32_e32 v18, v18, v23
	v_cvt_pk_bf16_f32 v18, v20, v18
	v_mul_f32_e32 v20, v71, v22
	v_add_f32_e32 v22, v20, v20
	v_cmp_nlt_f32_e32 vcc, s95, v22
	s_and_saveexec_b64 s[34:35], vcc
	s_xor_b64 s[36:37], exec, s[34:35]
	v_mul_f32_e32 v21, 0x3fb8aa3b, v22
	v_exp_f32_e32 v21, v21
	s_nop 0
	v_sub_f32_e32 v21, 1.0, v21
	s_andn2_saveexec_b64 s[36:37], s[36:37]
	v_fma_f32 v21, v22, 0.5, 1.0
	v_mul_f32_e64 v21, v21, -v22
	s_or_b64 exec, exec, s[36:37]
	v_add_f32_e32 v19, v19, v67
	v_mul_f32_e32 v19, 0xbfb8aa3b, v19
	v_exp_f32_e32 v19, v19
	v_max_f32_e32 v21, v21, v21
	v_max_f32_e32 v21, 0, v21
	v_sqrt_f32_e32 v21, v21
	v_add_f32_e32 v19, 1.0, v19
	v_rcp_f32_e32 v19, v19
	v_and_b32_e32 v22, 0xffff0000, v37
	v_mul_f32_e32 v19, v19, v21
	v_mul_f32_e32 v19, v19, v22
	v_cvt_pk_bf16_f32 v19, v20, v19
	v_mov_b64_e32 v[20:21], s[62:63]
	v_mad_i64_i32 v[20:21], s[34:35], v126, s87, v[20:21]
	v_lshl_add_u64 v[20:21], v[146:147], 2, v[20:21]
	global_store_dwordx4 v[20:21], v[16:19], off offset:64
	s_or_b64 exec, exec, s[22:23]
	s_and_saveexec_b64 s[22:23], s[52:53]
	s_cbranch_execz .LBB0_978
.LBB0_1013:
	s_waitcnt vmcnt(2)
	v_add_f32_e32 v12, v12, v72
	v_mul_f32_e32 v12, 0xbfb8aa3b, v12
	v_exp_f32_e32 v12, v12
	s_nop 0
	v_add_f32_e32 v12, 1.0, v12
	v_rcp_f32_e32 v12, v12
	s_nop 0
	v_mul_f32_e32 v12, v68, v12
	v_add_f32_e32 v17, v12, v12
	v_cmp_nlt_f32_e32 vcc, s95, v17
	s_and_saveexec_b64 s[34:35], vcc
	s_xor_b64 s[36:37], exec, s[34:35]
	v_mul_f32_e32 v16, 0x3fb8aa3b, v17
	v_exp_f32_e32 v16, v16
	s_nop 0
	v_sub_f32_e32 v16, 1.0, v16
	s_andn2_saveexec_b64 s[36:37], s[36:37]
	v_fma_f32 v16, v17, 0.5, 1.0
	v_mul_f32_e64 v16, v16, -v17
	s_or_b64 exec, exec, s[36:37]
	v_add_f32_e32 v8, v8, v64
	v_mul_f32_e32 v8, 0xbfb8aa3b, v8
	v_exp_f32_e32 v8, v8
	v_add_f32_e32 v13, v13, v73
	v_mul_f32_e32 v13, 0xbfb8aa3b, v13
	v_exp_f32_e32 v13, v13
	v_max_f32_e32 v16, v16, v16
	v_add_f32_e32 v8, 1.0, v8
	v_max_f32_e32 v16, 0, v16
	v_rcp_f32_e32 v8, v8
	v_sqrt_f32_e32 v16, v16
	v_add_f32_e32 v13, 1.0, v13
	v_rcp_f32_e32 v13, v13
	v_lshlrev_b32_e32 v17, 16, v34
	v_mul_f32_e32 v8, v8, v16
	v_mul_f32_e32 v8, v8, v17
	v_cvt_pk_bf16_f32 v8, v12, v8
	v_mul_f32_e32 v12, v69, v13
	v_add_f32_e32 v16, v12, v12
	v_cmp_nlt_f32_e32 vcc, s95, v16
	s_and_saveexec_b64 s[34:35], vcc
	s_xor_b64 s[36:37], exec, s[34:35]
	v_mul_f32_e32 v13, 0x3fb8aa3b, v16
	v_exp_f32_e32 v13, v13
	s_nop 0
	v_sub_f32_e32 v13, 1.0, v13
	s_andn2_saveexec_b64 s[36:37], s[36:37]
	v_fma_f32 v13, v16, 0.5, 1.0
	v_mul_f32_e64 v13, v13, -v16
	s_or_b64 exec, exec, s[36:37]
	v_add_f32_e32 v9, v9, v65
	v_mul_f32_e32 v9, 0xbfb8aa3b, v9
	v_exp_f32_e32 v9, v9
	v_add_f32_e32 v14, v14, v74
	v_mul_f32_e32 v14, 0xbfb8aa3b, v14
	v_exp_f32_e32 v14, v14
	v_max_f32_e32 v13, v13, v13
	v_add_f32_e32 v9, 1.0, v9
	v_max_f32_e32 v13, 0, v13
	v_rcp_f32_e32 v9, v9
	v_sqrt_f32_e32 v13, v13
	v_add_f32_e32 v14, 1.0, v14
; __device__ __forceinline__ unsigned cvt_pk_bf16(float lo, float hi) { unsigned r; asm volatile("v_cvt_pk_bf16_f32 %0, %1, %2" : "=v"(r) : "v"(lo), "v"(hi)); return r; }
; __device__ __forceinline__ float bflo(unsigned w) { return __uint_as_float(w << 16); }
; __device__ __forceinline__ float bfhi(unsigned w) { return __uint_as_float(w & 0xffff0000u); }
; __device__ __forceinline__ float fsigmoid(float x) { return __builtin_amdgcn_rcpf(1.0f + __expf(-x)); }
;     __device__ __forceinline__ void operator()(const f32x4 (&acc)[2][2][4][2], const Unit& u, int wr, int wc, int fr, int fq) const {
;     ...
;             for (int ai = 0; ai < 2; ++ai) { u32x2 xq[4];
; #pragma unroll
;                 for (int m = 0; m < 4; ++m) { const int row = row0 + ai * 128 + m * 16; xq[m] = *(const u32x2*)(XC + (size_t)(row < TT ? row : TT - 1) * DRNN + ch0 + 16 * n); }
; #pragma unroll
;                 for (int m = 0; m < 4; ++m) { const int row = row0 + ai * 128 + m * 16;
;                     if (row < TT) { const size_t off = (size_t)row * DRNN + ch0 + 16 * n; const u32x2 xw = xq[m]; const f32x4 xc = (f32x4){bflo(xw.x), bfhi(xw.x), bflo(xw.y), bfhi(xw.y)}; u32x4 o;
; #pragma unroll
;                         for (int i = 0; i < 4; ++i) { const float r = fsigmoid(acc[ai][0][m][n][i] + ba[i]), ig = fsigmoid(acc[ai][1][m][n][i] + bx[i]);
;                             const float la = r * lv[i], x2 = la + la, m = x2 > -1e-3f ? -x2 * fmaf(x2, 0.5f, 1.0f) : 1.0f - __expf(x2);
;                             o[i] = cvt_pk_bf16(la, __builtin_amdgcn_sqrtf(fmaxf(m, 0.0f)) * ig * xc[i]); }
;                         *(u32x4*)(AB + off) = o; } }
;                 asm volatile("" ::: "memory"); } }
	v_rcp_f32_e32 v14, v14
	v_and_b32_e32 v16, 0xffff0000, v34
	v_mul_f32_e32 v9, v9, v13
	v_mul_f32_e32 v9, v9, v16
	v_cvt_pk_bf16_f32 v9, v12, v9
	v_mul_f32_e32 v12, v70, v14
	v_add_f32_e32 v14, v12, v12
	v_cmp_nlt_f32_e32 vcc, s95, v14
	s_and_saveexec_b64 s[34:35], vcc
	s_xor_b64 s[36:37], exec, s[34:35]
	v_mul_f32_e32 v13, 0x3fb8aa3b, v14
	v_exp_f32_e32 v13, v13
	s_nop 0
	v_sub_f32_e32 v13, 1.0, v13
	s_andn2_saveexec_b64 s[36:37], s[36:37]
	v_fma_f32 v13, v14, 0.5, 1.0
	v_mul_f32_e64 v13, v13, -v14
	s_or_b64 exec, exec, s[36:37]
	v_add_f32_e32 v10, v10, v66
	v_mul_f32_e32 v10, 0xbfb8aa3b, v10
	v_exp_f32_e32 v10, v10
	v_add_f32_e32 v14, v15, v75
	v_mul_f32_e32 v14, 0xbfb8aa3b, v14
	v_exp_f32_e32 v14, v14
	v_max_f32_e32 v13, v13, v13
	v_add_f32_e32 v10, 1.0, v10
	v_max_f32_e32 v13, 0, v13
	v_rcp_f32_e32 v10, v10
	v_sqrt_f32_e32 v13, v13
	v_add_f32_e32 v14, 1.0, v14
	v_rcp_f32_e32 v14, v14
	v_lshlrev_b32_e32 v15, 16, v35
	v_mul_f32_e32 v10, v10, v13
	v_mul_f32_e32 v10, v10, v15
	v_cvt_pk_bf16_f32 v10, v12, v10
	v_mul_f32_e32 v12, v71, v14
	v_add_f32_e32 v14, v12, v12
	v_cmp_nlt_f32_e32 vcc, s95, v14
	s_and_saveexec_b64 s[34:35], vcc
	s_xor_b64 s[36:37], exec, s[34:35]
	v_mul_f32_e32 v13, 0x3fb8aa3b, v14
	v_exp_f32_e32 v13, v13
	s_nop 0
	v_sub_f32_e32 v13, 1.0, v13
	s_andn2_saveexec_b64 s[36:37], s[36:37]
	v_fma_f32 v13, v14, 0.5, 1.0
	v_mul_f32_e64 v13, v13, -v14
	s_or_b64 exec, exec, s[36:37]
	v_add_f32_e32 v11, v11, v67
	v_mul_f32_e32 v11, 0xbfb8aa3b, v11
	v_exp_f32_e32 v11, v11
	v_max_f32_e32 v13, v13, v13
	v_max_f32_e32 v13, 0, v13
	v_sqrt_f32_e32 v13, v13
	v_add_f32_e32 v11, 1.0, v11
	v_rcp_f32_e32 v11, v11
	v_and_b32_e32 v14, 0xffff0000, v35
	v_mul_f32_e32 v11, v11, v13
	v_mul_f32_e32 v11, v11, v14
	v_cvt_pk_bf16_f32 v11, v12, v11
	v_mov_b64_e32 v[12:13], s[62:63]
	v_mad_i64_i32 v[12:13], s[34:35], v125, s87, v[12:13]
	v_lshl_add_u64 v[12:13], v[146:147], 2, v[12:13]
	global_store_dwordx4 v[12:13], v[8:11], off offset:64
	s_or_b64 exec, exec, s[22:23]
	s_and_saveexec_b64 s[22:23], s[54:55]
	s_cbranch_execz .LBB0_1047
.LBB0_1030:
	s_waitcnt vmcnt(3)
	v_add_f32_e32 v4, v4, v72
	v_mul_f32_e32 v4, 0xbfb8aa3b, v4
	v_exp_f32_e32 v4, v4
	s_nop 0
	v_add_f32_e32 v4, 1.0, v4
	v_rcp_f32_e32 v4, v4
	s_nop 0
	v_mul_f32_e32 v4, v68, v4
	v_add_f32_e32 v9, v4, v4
	v_cmp_nlt_f32_e32 vcc, s95, v9
	s_and_saveexec_b64 s[34:35], vcc
	s_xor_b64 s[36:37], exec, s[34:35]
	v_mul_f32_e32 v8, 0x3fb8aa3b, v9
	v_exp_f32_e32 v8, v8
	s_nop 0
	v_sub_f32_e32 v8, 1.0, v8
	s_andn2_saveexec_b64 s[36:37], s[36:37]
	v_fma_f32 v8, v9, 0.5, 1.0
	v_mul_f32_e64 v8, v8, -v9
	s_or_b64 exec, exec, s[36:37]
	v_add_f32_e32 v0, v0, v64
	v_mul_f32_e32 v0, 0xbfb8aa3b, v0
	v_exp_f32_e32 v0, v0
	v_max_f32_e32 v8, v8, v8
	v_max_f32_e32 v8, 0, v8
	v_sqrt_f32_e32 v8, v8
	v_add_f32_e32 v0, 1.0, v0
	v_rcp_f32_e32 v0, v0
	v_lshlrev_b32_e32 v9, 16, v32
	v_mul_f32_e32 v0, v0, v8
	v_mul_f32_e32 v0, v0, v9
	v_cvt_pk_bf16_f32 v0, v4, v0
	v_add_f32_e32 v4, v5, v73
	v_mul_f32_e32 v4, 0xbfb8aa3b, v4
	v_exp_f32_e32 v4, v4
	s_nop 0
	v_add_f32_e32 v4, 1.0, v4
	v_rcp_f32_e32 v4, v4
	s_nop 0
	v_mul_f32_e32 v4, v69, v4
	v_add_f32_e32 v8, v4, v4
	v_cmp_nlt_f32_e32 vcc, s95, v8
	s_and_saveexec_b64 s[34:35], vcc
	s_xor_b64 s[36:37], exec, s[34:35]
	v_mul_f32_e32 v5, 0x3fb8aa3b, v8
	v_exp_f32_e32 v5, v5
	s_nop 0
	v_sub_f32_e32 v5, 1.0, v5
	s_andn2_saveexec_b64 s[36:37], s[36:37]
	v_fma_f32 v5, v8, 0.5, 1.0
	v_mul_f32_e64 v5, v5, -v8
	s_or_b64 exec, exec, s[36:37]
	v_add_f32_e32 v1, v1, v65
	v_mul_f32_e32 v1, 0xbfb8aa3b, v1
	v_exp_f32_e32 v1, v1
	v_add_f32_e32 v6, v6, v74
	v_mul_f32_e32 v6, 0xbfb8aa3b, v6
	v_exp_f32_e32 v6, v6
	v_max_f32_e32 v5, v5, v5
	v_add_f32_e32 v1, 1.0, v1
	v_max_f32_e32 v5, 0, v5
	v_rcp_f32_e32 v1, v1
	v_sqrt_f32_e32 v5, v5
	v_add_f32_e32 v6, 1.0, v6
	v_rcp_f32_e32 v6, v6
	v_and_b32_e32 v8, 0xffff0000, v32
	v_mul_f32_e32 v1, v1, v5
	v_mul_f32_e32 v1, v1, v8
	v_cvt_pk_bf16_f32 v1, v4, v1
	v_mul_f32_e32 v4, v70, v6
	v_add_f32_e32 v6, v4, v4
	v_cmp_nlt_f32_e32 vcc, s95, v6
	s_and_saveexec_b64 s[34:35], vcc
	s_xor_b64 s[36:37], exec, s[34:35]
	v_mul_f32_e32 v5, 0x3fb8aa3b, v6
	v_exp_f32_e32 v5, v5
	s_nop 0
	v_sub_f32_e32 v5, 1.0, v5
	s_andn2_saveexec_b64 s[36:37], s[36:37]
	v_fma_f32 v5, v6, 0.5, 1.0
	v_mul_f32_e64 v5, v5, -v6
	s_or_b64 exec, exec, s[36:37]
	v_add_f32_e32 v2, v2, v66
	v_mul_f32_e32 v2, 0xbfb8aa3b, v2
	v_exp_f32_e32 v2, v2
	v_add_f32_e32 v6, v7, v75
	v_mul_f32_e32 v6, 0xbfb8aa3b, v6
	v_exp_f32_e32 v6, v6
	v_max_f32_e32 v5, v5, v5
	v_add_f32_e32 v2, 1.0, v2
	v_max_f32_e32 v5, 0, v5
	v_rcp_f32_e32 v2, v2
	v_sqrt_f32_e32 v5, v5
	v_add_f32_e32 v6, 1.0, v6
	v_rcp_f32_e32 v6, v6
	v_lshlrev_b32_e32 v7, 16, v33
	v_mul_f32_e32 v2, v2, v5
	v_mul_f32_e32 v2, v2, v7
	v_cvt_pk_bf16_f32 v2, v4, v2
	v_mul_f32_e32 v4, v71, v6
	v_add_f32_e32 v6, v4, v4
	v_cmp_nlt_f32_e32 vcc, s95, v6
	s_and_saveexec_b64 s[34:35], vcc
	s_xor_b64 s[36:37], exec, s[34:35]
	v_mul_f32_e32 v5, 0x3fb8aa3b, v6
	v_exp_f32_e32 v5, v5
	s_nop 0
	v_sub_f32_e32 v5, 1.0, v5
	s_andn2_saveexec_b64 s[36:37], s[36:37]
	v_fma_f32 v5, v6, 0.5, 1.0
	v_mul_f32_e64 v5, v5, -v6
	s_or_b64 exec, exec, s[36:37]
	v_add_f32_e32 v3, v3, v67
	v_mul_f32_e32 v3, 0xbfb8aa3b, v3
	v_exp_f32_e32 v3, v3
	v_max_f32_e32 v5, v5, v5
	v_max_f32_e32 v5, 0, v5
	v_sqrt_f32_e32 v5, v5
	v_add_f32_e32 v3, 1.0, v3
	v_rcp_f32_e32 v3, v3
	v_and_b32_e32 v6, 0xffff0000, v33
	v_mul_f32_e32 v3, v3, v5
	v_mul_f32_e32 v3, v3, v6
	v_cvt_pk_bf16_f32 v3, v4, v3
	v_mov_b64_e32 v[4:5], s[62:63]
	v_mad_i64_i32 v[4:5], s[34:35], v124, s87, v[4:5]
	v_lshl_add_u64 v[4:5], v[146:147], 2, v[4:5]
	global_store_dwordx4 v[4:5], v[0:3], off offset:64

;     __device__ __forceinline__ int koffB(const Unit& u) const { return koff(u); }
;     __device__ __forceinline__ void a_ready(const Unit& u) const { wait_panel(cnt, u.pm, need, tmo, wave); }
;     __device__ __forceinline__ void a_ready(const Unit& u) const { wait_panel(cnt, u.pm, need, tmo, wave); }
; #define PG8_STAGE(bufoff, gbase, voff) do { _Pragma("unroll") for (int _i = 0; _i < 2; ++_i) \
;         __builtin_amdgcn_global_load_lds((const unsigned*)((const char*)(gbase) + (voff)[_i]), (PG8_LAS unsigned*)(lds + (bufoff) + ldsw + _i * 8192), 16, 0, 0); } while (0)
; #define PG8_WAIT_V(n) asm volatile("s_waitcnt vmcnt(" #n ")" ::: "memory")
; #define PG8_BAR __builtin_amdgcn_s_barrier()
; template <class Epi, class Sched, bool ALIGN_EPI = false, bool SP2 = false>
; __device__ __forceinline__ void gemm_phase(PG8_LAS unsigned char* lds, const Gemm g, const Sched& S, const Epi& E, const int tid_in) {
;     ...
;     const char* cA = (const char*)g.A + (size_t)cur.pm * tstepA + (size_t)S.koff(cur) * 2; const char* cB = (const char*)g.Bt + (size_t)cur.pn * tstepB + (size_t)S.koffB(cur) * 2;
;     S.a_ready(cur);
;     if constexpr (SP2) {
;         PG8_STAGE(PG8_SB(0, 0), cB, voffB); PG8_STAGE(PG8_SB(0, 1), cB + hstepB, voffB); PG8_STAGE(PG8_SA(0, 0), cA, voffA); PG8_STAGE(PG8_SA(0, 1), cA + hstepA, voffA);
;         if (wr == 1) PG8_BAR;
;         PG8_WAIT_V(2); PG8_BAR;
;         PG8_STAGE(PG8_SB(1, 0), cB + kstep, voffB); PG8_STAGE(PG8_SA(1, 0), cA + kstep, voffA); PG8_STAGE(PG8_SB(1, 1), cB + hstepB + kstep, voffB);
;         PG8_WAIT_V(6); PG8_BAR;
.LBB0_2306:
	v_lshrrev_b32_e32 v16, 1, v12
	v_and_b32_e32 v16, 24, v16
	v_and_b32_e32 v15, 15, v12
	v_lshlrev_b32_e32 v17, 1, v16
	v_lshlrev_b32_e32 v12, 2, v12
	v_lshl_or_b32 v140, s16, 6, v15
	v_lshl_or_b32 v15, v15, 6, v17
	s_lshl_b32 s16, s16, 13
	v_and_b32_e32 v12, 32, v12
	v_bitop3_b32 v17, v15, s16, v12 bitop3:0xde
	s_lshl_b32 s16, s17, 5
	s_and_b32 s33, s16, 0x60
	s_add_i32 m0, s37, 0x18000
	v_lshl_add_u64 v[6:7], v[6:7], 0, s[82:83]
	s_lshl_b32 s16, s33, 7
	s_waitcnt vmcnt(2)
	s_barrier
	global_load_lds_dwordx4 v[6:7], off
	v_lshl_add_u64 v[4:5], v[4:5], 0, s[82:83]
	s_add_i32 m0, s37, 0x1a000
	s_add_i32 s73, s37, 0x8000
	s_add_i32 s74, s37, 0xa000
	v_bitop3_b32 v141, v15, s16, v12 bitop3:0xde
	global_load_lds_dwordx4 v[4:5], off
	v_lshl_add_u64 v[0:1], v[0:1], 0, s[82:83]
	s_mov_b32 m0, s73
	s_add_u32 s16, s66, 0x80080
	global_load_lds_dwordx4 v[0:1], off
	v_lshl_add_u64 v[0:1], v[2:3], 0, s[82:83]
	s_mov_b32 m0, s74
	s_addc_u32 s17, s67, 0
	global_load_lds_dwordx4 v[0:1], off
	s_add_i32 m0, s37, 0x1c000
	v_lshl_add_u64 v[0:1], s[16:17], 0, v[172:173]
	global_load_lds_dwordx4 v[0:1], off
	v_lshl_add_u64 v[0:1], s[16:17], 0, v[132:133]
	s_add_i32 m0, s37, 0x1e000
	s_cmpk_lt_u32 s6, 0x100
	global_load_lds_dwordx4 v[0:1], off
	s_cselect_b64 s[48:49], -1, 0
	s_ashr_i32 s6, s31, 31
	v_lshlrev_b32_e32 v0, 15, v8
	s_lshr_b32 s6, s6, 29
	v_and_b32_e32 v0, 0xffff0000, v0
	s_add_i32 s6, s31, s6
	v_lshl_add_u32 v0, v9, 12, v0
	v_and_b32_e32 v1, 1, v8
	s_ashr_i32 s16, s6, 3
	s_and_b32 s6, s6, -8
	v_lshl_or_b32 v0, v1, 6, v0
	s_sub_i32 s6, s31, s6
	s_ashr_i32 s17, s15, 3
	v_lshl_add_u32 v134, v10, 1, v0
	v_lshlrev_b32_e32 v0, 15, v11
	s_mul_i32 s6, s17, s6
	v_and_b32_e32 v0, 0xffff0000, v0
	s_waitcnt vmcnt(6)
	s_add_i32 s6, s6, s16
	v_lshl_add_u32 v0, v13, 12, v0
	v_and_b32_e32 v1, 1, v11
	s_and_b64 s[16:17], s[22:23], exec
	v_lshl_or_b32 v0, v1, 6, v0
	s_mov_b32 s75, 0
	v_cmp_eq_u32_e64 s[40:41], 0, v214
	s_cselect_b32 s76, s6, s31
	v_or_b32_e32 v142, s33, v16
	v_mov_b32_e32 v135, v173
	v_lshl_add_u32 v136, v14, 1, v0
	v_mov_b32_e32 v137, v173
	v_add_u32_e32 v143, 0, v17
	s_barrier
	v_mov_b32_e32 v250, -1
	v_mov_b32_e32 v251, 1
	s_waitcnt vmcnt(0)
	s_branch .LBB0_2309

; __device__ __forceinline__ bool lane0() { return __builtin_amdgcn_mbcnt_hi(~0u, __builtin_amdgcn_mbcnt_lo(~0u, 0u)) == 0u; }
; __device__ __forceinline__ unsigned cvt_pk_bf16(float lo, float hi) { unsigned r; asm volatile("v_cvt_pk_bf16_f32 %0, %1, %2" : "=v"(r) : "v"(lo), "v"(hi)); return r; }
; __device__ __forceinline__ float fsilu(float x) { return x * fsigmoid(x); }
;     __device__ __forceinline__ void done(const Unit& u) const { asm volatile("s_waitcnt vmcnt(0)" ::: "memory"); if (lane0()) __hip_atomic_fetch_add(cnt + 64 * u.pm, 1u, __ATOMIC_RELAXED, __HIP_MEMORY_SCOPE_AGENT); }
;     __device__ __forceinline__ void operator()(const f32x4 (&acc)[2][2][4][2], const Unit& u, int wr, int wc, int fr, int fq) const {
;         const int row0 = u.pm * 256 + wr * 64 + fr, col0 = u.pn * 128 + wc * 32 + 8 * fq;
; #pragma unroll
;         for (int ai = 0; ai < 2; ++ai)
; #pragma unroll
;             for (int m = 0; m < 4; ++m) { bf16* rowp = O + (size_t)(row0 + ai * 128 + m * 16) * DFF + col0;
;                 float h[8];
; #pragma unroll
;                 for (int n = 0; n < 2; ++n)
; #pragma unroll
;                     for (int i = 0; i < 4; ++i) h[4 * n + i] = fsilu(acc[ai][0][m][n][i]) * acc[ai][1][m][n][i];
;                 u32x4 w; w.x = cvt_pk_bf16(h[0], h[1]); w.y = cvt_pk_bf16(h[2], h[3]); w.z = cvt_pk_bf16(h[4], h[5]); w.w = cvt_pk_bf16(h[6], h[7]);
;                 asm volatile("global_store_dwordx4 %0, %1, off sc1\n\ts_nop 1" :: "v"(rowp), "v"(w) : "memory"); }
.LBB0_2315:
	v_readlane_b32 s16, v250, 0
	s_nop 3
	s_cmp_lt_i32 s16, 0
	s_cbranch_scc1 .Lgu_no_pending
	s_lshl_b32 s16, s16, 8
	s_add_u32 s16, s38, s16
	s_addc_u32 s17, s30, 0
	s_mov_b64 s[22:23], exec
	s_mov_b64 exec, s[40:41]
	global_atomic_add v173, v251, s[16:17]
	s_mov_b64 exec, s[22:23]
	s_mov_b32 s16, -1
	v_writelane_b32 v250, s16, 0
.Lgu_no_pending:
	v_mul_f32_e32 v145, 0xbfb8aa3b, v124
	v_exp_f32_e32 v145, v145
	v_lshl_or_b32 v146, s62, 7, v142
	v_lshl_add_u32 v144, s36, 8, v140
	v_ashrrev_i32_e32 v147, 31, v146
	v_add_f32_e32 v145, 1.0, v145
	v_rcp_f32_e32 v145, v145
	v_mov_b64_e32 v[138:139], s[46:47]
	v_mad_i64_i32 v[148:149], s[16:17], v144, s92, v[138:139]
	v_mul_f32_e32 v124, v124, v145
	v_mul_f32_e32 v120, v124, v120
	v_mul_f32_e32 v124, 0xbfb8aa3b, v125
	v_exp_f32_e32 v124, v124
	s_nop 0
	v_add_f32_e32 v124, 1.0, v124
	v_rcp_f32_e32 v124, v124
	s_nop 0
	v_mul_f32_e32 v124, v125, v124
	v_mul_f32_e32 v121, v124, v121
	v_mul_f32_e32 v124, 0xbfb8aa3b, v126
	v_exp_f32_e32 v124, v124
	s_nop 0
	v_add_f32_e32 v124, 1.0, v124
	v_rcp_f32_e32 v124, v124
	s_nop 0
	v_mul_f32_e32 v124, v126, v124
	v_mul_f32_e32 v122, v124, v122
	v_mul_f32_e32 v124, 0xbfb8aa3b, v127
	v_exp_f32_e32 v124, v124
	s_nop 0
	v_add_f32_e32 v124, 1.0, v124
	v_rcp_f32_e32 v124, v124
	s_nop 0
	v_mul_f32_e32 v124, v127, v124
	v_mul_f32_e32 v123, v124, v123
	v_mul_f32_e32 v124, 0xbfb8aa3b, v116
	v_exp_f32_e32 v124, v124
	s_nop 0
	v_add_f32_e32 v124, 1.0, v124
	v_rcp_f32_e32 v124, v124
	s_nop 0
	v_mul_f32_e32 v116, v116, v124
	v_mul_f32_e32 v116, v116, v112
	v_mul_f32_e32 v112, 0xbfb8aa3b, v117
	v_exp_f32_e32 v112, v112
	s_nop 0
	v_add_f32_e32 v112, 1.0, v112
	v_rcp_f32_e32 v112, v112
	s_nop 0
	v_mul_f32_e32 v112, v117, v112
	v_mul_f32_e32 v117, v112, v113
	v_mul_f32_e32 v112, 0xbfb8aa3b, v118
	v_exp_f32_e32 v112, v112
	s_nop 0
	v_add_f32_e32 v112, 1.0, v112
	v_rcp_f32_e32 v112, v112
	s_nop 0
	v_mul_f32_e32 v112, v118, v112
	v_mul_f32_e32 v124, v112, v114
	v_mul_f32_e32 v112, 0xbfb8aa3b, v119
	v_exp_f32_e32 v112, v112
	v_cvt_pk_bf16_f32 v114, v120, v121
	s_nop 0
	v_add_f32_e32 v112, 1.0, v112
	v_rcp_f32_e32 v112, v112
	s_nop 0
	v_mul_f32_e32 v112, v119, v112
	v_mul_f32_e32 v125, v112, v115
	v_lshlrev_b64 v[112:113], 1, v[146:147]
	v_cvt_pk_bf16_f32 v115, v122, v123
	v_cvt_pk_bf16_f32 v116, v116, v117
	v_lshl_add_u64 v[118:119], v[148:149], 0, v[112:113]
	v_cvt_pk_bf16_f32 v117, v124, v125
	s_nop 0
	global_store_dwordx4 v[118:119], v[114:117], off sc1
	s_nop 1
	v_mul_f32_e32 v116, 0xbfb8aa3b, v108
	v_exp_f32_e32 v116, v116
	v_or_b32_e32 v114, 16, v144
	v_mad_i64_i32 v[114:115], s[16:17], v114, s92, v[138:139]
	v_add_f32_e32 v116, 1.0, v116
	v_rcp_f32_e32 v116, v116
	s_nop 0
	v_mul_f32_e32 v108, v108, v116
	v_mul_f32_e32 v104, v108, v104
	v_mul_f32_e32 v108, 0xbfb8aa3b, v109
	v_exp_f32_e32 v108, v108
	s_nop 0
	v_add_f32_e32 v108, 1.0, v108
	v_rcp_f32_e32 v108, v108
	s_nop 0
	v_mul_f32_e32 v108, v109, v108
	v_mul_f32_e32 v105, v108, v105
	v_mul_f32_e32 v108, 0xbfb8aa3b, v110
	v_exp_f32_e32 v108, v108
	s_nop 0
	v_add_f32_e32 v108, 1.0, v108
	v_rcp_f32_e32 v108, v108
	s_nop 0
	v_mul_f32_e32 v108, v110, v108
	v_mul_f32_e32 v106, v108, v106
	v_mul_f32_e32 v108, 0xbfb8aa3b, v111
	v_exp_f32_e32 v108, v108
	s_nop 0
	v_add_f32_e32 v108, 1.0, v108
	v_rcp_f32_e32 v108, v108
	s_nop 0
	v_mul_f32_e32 v108, v111, v108
	v_mul_f32_e32 v107, v108, v107
	v_mul_f32_e32 v108, 0xbfb8aa3b, v100
	v_exp_f32_e32 v108, v108
	s_nop 0
	v_add_f32_e32 v108, 1.0, v108
	v_rcp_f32_e32 v108, v108
	s_nop 0
	v_mul_f32_e32 v100, v100, v108
	v_mul_f32_e32 v108, v100, v96
	v_mul_f32_e32 v96, 0xbfb8aa3b, v101
	v_exp_f32_e32 v96, v96
	s_nop 0
	v_add_f32_e32 v96, 1.0, v96
	v_rcp_f32_e32 v96, v96
	s_nop 0
	v_mul_f32_e32 v96, v101, v96
	v_mul_f32_e32 v109, v96, v97
	v_mul_f32_e32 v96, 0xbfb8aa3b, v102
	v_exp_f32_e32 v96, v96
	v_lshl_add_u64 v[100:101], v[114:115], 0, v[112:113]
	v_add_f32_e32 v96, 1.0, v96
	v_rcp_f32_e32 v96, v96
	s_nop 0
	v_mul_f32_e32 v96, v102, v96
	v_mul_f32_e32 v102, v96, v98
	v_mul_f32_e32 v96, 0xbfb8aa3b, v103
	v_exp_f32_e32 v96, v96
	s_nop 0
	v_add_f32_e32 v96, 1.0, v96
	v_rcp_f32_e32 v96, v96
	s_nop 0
	v_mul_f32_e32 v96, v103, v96
	v_mul_f32_e32 v99, v96, v99
	v_cvt_pk_bf16_f32 v96, v104, v105
	v_cvt_pk_bf16_f32 v97, v106, v107
	v_cvt_pk_bf16_f32 v98, v108, v109
	v_cvt_pk_bf16_f32 v99, v102, v99
	s_nop 0
	global_store_dwordx4 v[100:101], v[96:99], off sc1
	s_nop 1
	v_mul_f32_e32 v98, 0xbfb8aa3b, v92
	v_exp_f32_e32 v98, v98
	v_or_b32_e32 v96, 32, v144
	v_mad_i64_i32 v[96:97], s[16:17], v96, s92, v[138:139]
	v_add_f32_e32 v98, 1.0, v98
	v_rcp_f32_e32 v98, v98
	s_nop 0
	v_mul_f32_e32 v92, v92, v98
	v_mul_f32_e32 v88, v92, v88
	v_mul_f32_e32 v92, 0xbfb8aa3b, v93
	v_exp_f32_e32 v92, v92
	s_nop 0
	v_add_f32_e32 v92, 1.0, v92
	v_rcp_f32_e32 v92, v92
	s_nop 0
	v_mul_f32_e32 v92, v93, v92
	v_mul_f32_e32 v89, v92, v89
	v_mul_f32_e32 v92, 0xbfb8aa3b, v94
	v_exp_f32_e32 v92, v92
	s_nop 0
	v_add_f32_e32 v92, 1.0, v92
	v_rcp_f32_e32 v92, v92
	s_nop 0
	v_mul_f32_e32 v92, v94, v92
	v_mul_f32_e32 v90, v92, v90
	v_mul_f32_e32 v92, 0xbfb8aa3b, v95
	v_exp_f32_e32 v92, v92
	s_nop 0
	v_add_f32_e32 v92, 1.0, v92
	v_rcp_f32_e32 v92, v92
	s_nop 0
	v_mul_f32_e32 v92, v95, v92
	v_mul_f32_e32 v91, v92, v91
	v_mul_f32_e32 v92, 0xbfb8aa3b, v84
	v_exp_f32_e32 v92, v92
	s_nop 0
	v_add_f32_e32 v92, 1.0, v92
	v_rcp_f32_e32 v92, v92
	s_nop 0
	v_mul_f32_e32 v84, v84, v92
	v_mul_f32_e32 v92, v84, v80
	v_mul_f32_e32 v80, 0xbfb8aa3b, v85
	v_exp_f32_e32 v80, v80
	s_nop 0
	v_add_f32_e32 v80, 1.0, v80
	v_rcp_f32_e32 v80, v80
	s_nop 0
	v_mul_f32_e32 v80, v85, v80
	v_mul_f32_e32 v93, v80, v81
	v_mul_f32_e32 v80, 0xbfb8aa3b, v86
; __device__ __forceinline__ unsigned cvt_pk_bf16(float lo, float hi) { unsigned r; asm volatile("v_cvt_pk_bf16_f32 %0, %1, %2" : "=v"(r) : "v"(lo), "v"(hi)); return r; }
; __device__ __forceinline__ float fsilu(float x) { return x * fsigmoid(x); }
;     __device__ __forceinline__ void operator()(const f32x4 (&acc)[2][2][4][2], const Unit& u, int wr, int wc, int fr, int fq) const {
;     ...
;             for (int m = 0; m < 4; ++m) { bf16* rowp = O + (size_t)(row0 + ai * 128 + m * 16) * DFF + col0;
;                 float h[8];
; #pragma unroll
;                 for (int n = 0; n < 2; ++n)
; #pragma unroll
;                     for (int i = 0; i < 4; ++i) h[4 * n + i] = fsilu(acc[ai][0][m][n][i]) * acc[ai][1][m][n][i];
;                 u32x4 w; w.x = cvt_pk_bf16(h[0], h[1]); w.y = cvt_pk_bf16(h[2], h[3]); w.z = cvt_pk_bf16(h[4], h[5]); w.w = cvt_pk_bf16(h[6], h[7]);
;                 asm volatile("global_store_dwordx4 %0, %1, off sc1\n\ts_nop 1" :: "v"(rowp), "v"(w) : "memory"); }
	v_exp_f32_e32 v80, v80
	v_lshl_add_u64 v[84:85], v[96:97], 0, v[112:113]
	v_add_f32_e32 v80, 1.0, v80
	v_rcp_f32_e32 v80, v80
	s_nop 0
	v_mul_f32_e32 v80, v86, v80
	v_mul_f32_e32 v86, v80, v82
	v_mul_f32_e32 v80, 0xbfb8aa3b, v87
	v_exp_f32_e32 v80, v80
	s_nop 0
	v_add_f32_e32 v80, 1.0, v80
	v_rcp_f32_e32 v80, v80
	s_nop 0
	v_mul_f32_e32 v80, v87, v80
	v_mul_f32_e32 v83, v80, v83
	v_cvt_pk_bf16_f32 v80, v88, v89
	v_cvt_pk_bf16_f32 v81, v90, v91
	v_cvt_pk_bf16_f32 v82, v92, v93
	v_cvt_pk_bf16_f32 v83, v86, v83
	s_nop 0
	global_store_dwordx4 v[84:85], v[80:83], off sc1
	s_nop 1
	v_mul_f32_e32 v82, 0xbfb8aa3b, v76
	v_exp_f32_e32 v82, v82
	v_or_b32_e32 v80, 48, v144
	v_mad_i64_i32 v[80:81], s[16:17], v80, s92, v[138:139]
	v_add_f32_e32 v82, 1.0, v82
	v_rcp_f32_e32 v82, v82
	s_nop 0
	v_mul_f32_e32 v76, v76, v82
	v_mul_f32_e32 v72, v76, v72
	v_mul_f32_e32 v76, 0xbfb8aa3b, v77
	v_exp_f32_e32 v76, v76
	s_nop 0
	v_add_f32_e32 v76, 1.0, v76
	v_rcp_f32_e32 v76, v76
	s_nop 0
	v_mul_f32_e32 v76, v77, v76
	v_mul_f32_e32 v73, v76, v73
	v_mul_f32_e32 v76, 0xbfb8aa3b, v78
	v_exp_f32_e32 v76, v76
	s_nop 0
	v_add_f32_e32 v76, 1.0, v76
	v_rcp_f32_e32 v76, v76
	s_nop 0
	v_mul_f32_e32 v76, v78, v76
	v_mul_f32_e32 v74, v76, v74
	v_mul_f32_e32 v76, 0xbfb8aa3b, v79
	v_exp_f32_e32 v76, v76
	s_nop 0
	v_add_f32_e32 v76, 1.0, v76
	v_rcp_f32_e32 v76, v76
	s_nop 0
	v_mul_f32_e32 v76, v79, v76
	v_mul_f32_e32 v75, v76, v75
	v_mul_f32_e32 v76, 0xbfb8aa3b, v68
	v_exp_f32_e32 v76, v76
	s_nop 0
	v_add_f32_e32 v76, 1.0, v76
	v_rcp_f32_e32 v76, v76
	s_nop 0
	v_mul_f32_e32 v68, v68, v76
	v_mul_f32_e32 v76, v68, v64
	v_mul_f32_e32 v64, 0xbfb8aa3b, v69
	v_exp_f32_e32 v64, v64
	s_nop 0
	v_add_f32_e32 v64, 1.0, v64
	v_rcp_f32_e32 v64, v64
	s_nop 0
	v_mul_f32_e32 v64, v69, v64
	v_mul_f32_e32 v77, v64, v65
	v_mul_f32_e32 v64, 0xbfb8aa3b, v70
	v_exp_f32_e32 v64, v64
	v_lshl_add_u64 v[68:69], v[80:81], 0, v[112:113]
	v_add_f32_e32 v64, 1.0, v64
	v_rcp_f32_e32 v64, v64
	s_nop 0
	v_mul_f32_e32 v64, v70, v64
	v_mul_f32_e32 v70, v64, v66
	v_mul_f32_e32 v64, 0xbfb8aa3b, v71
	v_exp_f32_e32 v64, v64
	s_nop 0
	v_add_f32_e32 v64, 1.0, v64
	v_rcp_f32_e32 v64, v64
	s_nop 0
	v_mul_f32_e32 v64, v71, v64
	v_mul_f32_e32 v67, v64, v67
	v_cvt_pk_bf16_f32 v64, v72, v73
	v_cvt_pk_bf16_f32 v65, v74, v75
	v_cvt_pk_bf16_f32 v66, v76, v77
	v_cvt_pk_bf16_f32 v67, v70, v67
	s_nop 0
	global_store_dwordx4 v[68:69], v[64:67], off sc1
	s_nop 1
	v_mul_f32_e32 v66, 0xbfb8aa3b, v60
	v_exp_f32_e32 v66, v66
	v_add_u32_e32 v64, 0x80, v144
	v_mad_i64_i32 v[64:65], s[16:17], v64, s92, v[138:139]
	v_add_f32_e32 v66, 1.0, v66
	v_rcp_f32_e32 v66, v66
	s_nop 0
	v_mul_f32_e32 v60, v60, v66
	v_mul_f32_e32 v56, v60, v56
	v_mul_f32_e32 v60, 0xbfb8aa3b, v61
	v_exp_f32_e32 v60, v60
	s_nop 0
	v_add_f32_e32 v60, 1.0, v60
	v_rcp_f32_e32 v60, v60
	s_nop 0
	v_mul_f32_e32 v60, v61, v60
	v_mul_f32_e32 v57, v60, v57
	v_mul_f32_e32 v60, 0xbfb8aa3b, v62
	v_exp_f32_e32 v60, v60
	s_nop 0
	v_add_f32_e32 v60, 1.0, v60
	v_rcp_f32_e32 v60, v60
	s_nop 0
	v_mul_f32_e32 v60, v62, v60
	v_mul_f32_e32 v58, v60, v58
	v_mul_f32_e32 v60, 0xbfb8aa3b, v63
	v_exp_f32_e32 v60, v60
	s_nop 0
	v_add_f32_e32 v60, 1.0, v60
	v_rcp_f32_e32 v60, v60
	s_nop 0
	v_mul_f32_e32 v60, v63, v60
	v_mul_f32_e32 v59, v60, v59
	v_mul_f32_e32 v60, 0xbfb8aa3b, v52
	v_exp_f32_e32 v60, v60
	s_nop 0
	v_add_f32_e32 v60, 1.0, v60
	v_rcp_f32_e32 v60, v60
	s_nop 0
	v_mul_f32_e32 v52, v52, v60
	v_mul_f32_e32 v60, v52, v48
	v_mul_f32_e32 v48, 0xbfb8aa3b, v53
	v_exp_f32_e32 v48, v48
	s_nop 0
	v_add_f32_e32 v48, 1.0, v48
	v_rcp_f32_e32 v48, v48
	s_nop 0
	v_mul_f32_e32 v48, v53, v48
	v_mul_f32_e32 v61, v48, v49
	v_mul_f32_e32 v48, 0xbfb8aa3b, v54
	v_exp_f32_e32 v48, v48
	v_lshl_add_u64 v[52:53], v[64:65], 0, v[112:113]
	v_add_f32_e32 v48, 1.0, v48
	v_rcp_f32_e32 v48, v48
	s_nop 0
	v_mul_f32_e32 v48, v54, v48
	v_mul_f32_e32 v54, v48, v50
	v_mul_f32_e32 v48, 0xbfb8aa3b, v55
	v_exp_f32_e32 v48, v48
	s_nop 0
	v_add_f32_e32 v48, 1.0, v48
	v_rcp_f32_e32 v48, v48
	s_nop 0
	v_mul_f32_e32 v48, v55, v48
	v_mul_f32_e32 v51, v48, v51
	v_cvt_pk_bf16_f32 v48, v56, v57
	v_cvt_pk_bf16_f32 v49, v58, v59
	v_cvt_pk_bf16_f32 v50, v60, v61
	v_cvt_pk_bf16_f32 v51, v54, v51
	s_nop 0
	global_store_dwordx4 v[52:53], v[48:51], off sc1
	s_nop 1
	v_mul_f32_e32 v50, 0xbfb8aa3b, v44
	v_exp_f32_e32 v50, v50
	v_add_u32_e32 v48, 0x90, v144
	v_mad_i64_i32 v[48:49], s[16:17], v48, s92, v[138:139]
	v_add_f32_e32 v50, 1.0, v50
	v_rcp_f32_e32 v50, v50
	s_nop 0
	v_mul_f32_e32 v44, v44, v50
	v_mul_f32_e32 v40, v44, v40
	v_mul_f32_e32 v44, 0xbfb8aa3b, v45
	v_exp_f32_e32 v44, v44
	s_nop 0
	v_add_f32_e32 v44, 1.0, v44
	v_rcp_f32_e32 v44, v44
	s_nop 0
	v_mul_f32_e32 v44, v45, v44
	v_mul_f32_e32 v41, v44, v41
	v_mul_f32_e32 v44, 0xbfb8aa3b, v46
	v_exp_f32_e32 v44, v44
	s_nop 0
	v_add_f32_e32 v44, 1.0, v44
	v_rcp_f32_e32 v44, v44
	s_nop 0
	v_mul_f32_e32 v44, v46, v44
	v_mul_f32_e32 v42, v44, v42
	v_mul_f32_e32 v44, 0xbfb8aa3b, v47
	v_exp_f32_e32 v44, v44
	s_nop 0
	v_add_f32_e32 v44, 1.0, v44
	v_rcp_f32_e32 v44, v44
	s_nop 0
	v_mul_f32_e32 v44, v47, v44
	v_mul_f32_e32 v43, v44, v43
	v_mul_f32_e32 v44, 0xbfb8aa3b, v36
	v_exp_f32_e32 v44, v44
	s_nop 0
; __device__ __forceinline__ bool lane0() { return __builtin_amdgcn_mbcnt_hi(~0u, __builtin_amdgcn_mbcnt_lo(~0u, 0u)) == 0u; }
; __device__ __forceinline__ unsigned cvt_pk_bf16(float lo, float hi) { unsigned r; asm volatile("v_cvt_pk_bf16_f32 %0, %1, %2" : "=v"(r) : "v"(lo), "v"(hi)); return r; }
; __device__ __forceinline__ float fsilu(float x) { return x * fsigmoid(x); }
;     __device__ __forceinline__ void done(const Unit& u) const { asm volatile("s_waitcnt vmcnt(0)" ::: "memory"); if (lane0()) __hip_atomic_fetch_add(cnt + 64 * u.pm, 1u, __ATOMIC_RELAXED, __HIP_MEMORY_SCOPE_AGENT); }
;     __device__ __forceinline__ void operator()(const f32x4 (&acc)[2][2][4][2], const Unit& u, int wr, int wc, int fr, int fq) const {
;     ...
;                 for (int n = 0; n < 2; ++n)
; #pragma unroll
;                     for (int i = 0; i < 4; ++i) h[4 * n + i] = fsilu(acc[ai][0][m][n][i]) * acc[ai][1][m][n][i];
;                 u32x4 w; w.x = cvt_pk_bf16(h[0], h[1]); w.y = cvt_pk_bf16(h[2], h[3]); w.z = cvt_pk_bf16(h[4], h[5]); w.w = cvt_pk_bf16(h[6], h[7]);
;                 asm volatile("global_store_dwordx4 %0, %1, off sc1\n\ts_nop 1" :: "v"(rowp), "v"(w) : "memory"); }
	v_add_f32_e32 v44, 1.0, v44
	v_rcp_f32_e32 v44, v44
	s_nop 0
	v_mul_f32_e32 v36, v36, v44
	v_mul_f32_e32 v44, v36, v32
	v_mul_f32_e32 v32, 0xbfb8aa3b, v37
	v_exp_f32_e32 v32, v32
	s_nop 0
	v_add_f32_e32 v32, 1.0, v32
	v_rcp_f32_e32 v32, v32
	s_nop 0
	v_mul_f32_e32 v32, v37, v32
	v_mul_f32_e32 v45, v32, v33
	v_mul_f32_e32 v32, 0xbfb8aa3b, v38
	v_exp_f32_e32 v32, v32
	v_lshl_add_u64 v[36:37], v[48:49], 0, v[112:113]
	v_add_f32_e32 v32, 1.0, v32
	v_rcp_f32_e32 v32, v32
	s_nop 0
	v_mul_f32_e32 v32, v38, v32
	v_mul_f32_e32 v38, v32, v34
	v_mul_f32_e32 v32, 0xbfb8aa3b, v39
	v_exp_f32_e32 v32, v32
	s_nop 0
	v_add_f32_e32 v32, 1.0, v32
	v_rcp_f32_e32 v32, v32
	s_nop 0
	v_mul_f32_e32 v32, v39, v32
	v_mul_f32_e32 v35, v32, v35
	v_cvt_pk_bf16_f32 v32, v40, v41
	v_cvt_pk_bf16_f32 v33, v42, v43
	v_cvt_pk_bf16_f32 v34, v44, v45
	v_cvt_pk_bf16_f32 v35, v38, v35
	s_nop 0
	global_store_dwordx4 v[36:37], v[32:35], off sc1
	s_nop 1
	v_mul_f32_e32 v34, 0xbfb8aa3b, v28
	v_exp_f32_e32 v34, v34
	v_add_u32_e32 v32, 0xa0, v144
	v_mad_i64_i32 v[32:33], s[16:17], v32, s92, v[138:139]
	v_add_f32_e32 v34, 1.0, v34
	v_rcp_f32_e32 v34, v34
	s_nop 0
	v_mul_f32_e32 v28, v28, v34
	v_mul_f32_e32 v24, v28, v24
	v_mul_f32_e32 v28, 0xbfb8aa3b, v29
	v_exp_f32_e32 v28, v28
	s_nop 0
	v_add_f32_e32 v28, 1.0, v28
	v_rcp_f32_e32 v28, v28
	s_nop 0
	v_mul_f32_e32 v28, v29, v28
	v_mul_f32_e32 v25, v28, v25
	v_mul_f32_e32 v28, 0xbfb8aa3b, v30
	v_exp_f32_e32 v28, v28
	s_nop 0
	v_add_f32_e32 v28, 1.0, v28
	v_rcp_f32_e32 v28, v28
	s_nop 0
	v_mul_f32_e32 v28, v30, v28
	v_mul_f32_e32 v26, v28, v26
	v_mul_f32_e32 v28, 0xbfb8aa3b, v31
	v_exp_f32_e32 v28, v28
	s_nop 0
	v_add_f32_e32 v28, 1.0, v28
	v_rcp_f32_e32 v28, v28
	s_nop 0
	v_mul_f32_e32 v28, v31, v28
	v_mul_f32_e32 v27, v28, v27
	v_mul_f32_e32 v28, 0xbfb8aa3b, v20
	v_exp_f32_e32 v28, v28
	s_nop 0
	v_add_f32_e32 v28, 1.0, v28
	v_rcp_f32_e32 v28, v28
	s_nop 0
	v_mul_f32_e32 v20, v20, v28
	v_mul_f32_e32 v28, v20, v16
	v_mul_f32_e32 v16, 0xbfb8aa3b, v21
	v_exp_f32_e32 v16, v16
	s_nop 0
	v_add_f32_e32 v16, 1.0, v16
	v_rcp_f32_e32 v16, v16
	s_nop 0
	v_mul_f32_e32 v16, v21, v16
	v_mul_f32_e32 v29, v16, v17
	v_mul_f32_e32 v16, 0xbfb8aa3b, v22
	v_exp_f32_e32 v16, v16
	v_lshl_add_u64 v[20:21], v[32:33], 0, v[112:113]
	v_add_f32_e32 v16, 1.0, v16
	v_rcp_f32_e32 v16, v16
	s_nop 0
	v_mul_f32_e32 v16, v22, v16
	v_mul_f32_e32 v22, v16, v18
	v_mul_f32_e32 v16, 0xbfb8aa3b, v23
	v_exp_f32_e32 v16, v16
	s_nop 0
	v_add_f32_e32 v16, 1.0, v16
	v_rcp_f32_e32 v16, v16
	s_nop 0
	v_mul_f32_e32 v16, v23, v16
	v_mul_f32_e32 v19, v16, v19
	v_cvt_pk_bf16_f32 v16, v24, v25
	v_cvt_pk_bf16_f32 v17, v26, v27
	v_cvt_pk_bf16_f32 v18, v28, v29
	v_cvt_pk_bf16_f32 v19, v22, v19
	s_nop 0
	global_store_dwordx4 v[20:21], v[16:19], off sc1
	s_nop 1
	v_mul_f32_e32 v18, 0xbfb8aa3b, v12
	v_exp_f32_e32 v18, v18
	v_add_u32_e32 v16, 0xb0, v144
	v_mad_i64_i32 v[16:17], s[16:17], v16, s92, v[138:139]
	v_add_f32_e32 v18, 1.0, v18
	v_rcp_f32_e32 v18, v18
	s_nop 0
	v_mul_f32_e32 v12, v12, v18
	v_mul_f32_e32 v8, v12, v8
	v_mul_f32_e32 v12, 0xbfb8aa3b, v13
	v_exp_f32_e32 v12, v12
	s_nop 0
	v_add_f32_e32 v12, 1.0, v12
	v_rcp_f32_e32 v12, v12
	s_nop 0
	v_mul_f32_e32 v12, v13, v12
	v_mul_f32_e32 v9, v12, v9
	v_mul_f32_e32 v12, 0xbfb8aa3b, v14
	v_exp_f32_e32 v12, v12
	s_nop 0
	v_add_f32_e32 v12, 1.0, v12
	v_rcp_f32_e32 v12, v12
	s_nop 0
	v_mul_f32_e32 v12, v14, v12
	v_mul_f32_e32 v10, v12, v10
	v_mul_f32_e32 v12, 0xbfb8aa3b, v15
	v_exp_f32_e32 v12, v12
	s_nop 0
	v_add_f32_e32 v12, 1.0, v12
	v_rcp_f32_e32 v12, v12
	s_nop 0
	v_mul_f32_e32 v12, v15, v12
	v_mul_f32_e32 v11, v12, v11
	v_mul_f32_e32 v12, 0xbfb8aa3b, v4
	v_exp_f32_e32 v12, v12
	s_nop 0
	v_add_f32_e32 v12, 1.0, v12
	v_rcp_f32_e32 v12, v12
	s_nop 0
	v_mul_f32_e32 v4, v4, v12
	v_mul_f32_e32 v12, v4, v0
	v_mul_f32_e32 v0, 0xbfb8aa3b, v5
	v_exp_f32_e32 v0, v0
	s_nop 0
	v_add_f32_e32 v0, 1.0, v0
	v_rcp_f32_e32 v0, v0
	s_nop 0
	v_mul_f32_e32 v0, v5, v0
	v_mul_f32_e32 v13, v0, v1
	v_mul_f32_e32 v0, 0xbfb8aa3b, v6
	v_exp_f32_e32 v0, v0
	v_lshl_add_u64 v[4:5], v[16:17], 0, v[112:113]
	v_add_f32_e32 v0, 1.0, v0
	v_rcp_f32_e32 v0, v0
	s_nop 0
	v_mul_f32_e32 v0, v6, v0
	v_mul_f32_e32 v6, v0, v2
	v_mul_f32_e32 v0, 0xbfb8aa3b, v7
	v_exp_f32_e32 v0, v0
	s_nop 0
	v_add_f32_e32 v0, 1.0, v0
	v_rcp_f32_e32 v0, v0
	s_nop 0
	v_mul_f32_e32 v0, v7, v0
	v_mul_f32_e32 v3, v0, v3
	v_cvt_pk_bf16_f32 v0, v8, v9
	v_cvt_pk_bf16_f32 v1, v10, v11
	v_cvt_pk_bf16_f32 v2, v12, v13
	v_cvt_pk_bf16_f32 v3, v6, v3
	s_nop 0
	global_store_dwordx4 v[4:5], v[0:3], off sc1
	s_nop 1
	s_and_b64 vcc, exec, s[56:57]
	s_cbranch_vccz .Lgu_drain_now
	v_writelane_b32 v250, s36, 0
	s_branch .Lgu_defer_join
.Lgu_drain_now:
	s_waitcnt vmcnt(0)
	s_and_saveexec_b64 s[22:23], s[40:41]
	s_cbranch_execz .LBB0_2318
	s_mov_b64 s[62:63], exec
	v_mbcnt_lo_u32_b32 v0, s62, 0
	v_mbcnt_hi_u32_b32 v0, s63, v0
	v_cmp_eq_u32_e32 vcc, 0, v0
	s_and_b64 s[16:17], exec, vcc
	s_mov_b64 exec, s[16:17]
	s_cbranch_execz .LBB0_2318
	s_lshl_b32 s16, s36, 6
	s_ashr_i32 s17, s16, 31
	s_lshl_b64 s[16:17], s[16:17], 2
	s_add_u32 s16, s38, s16
	s_addc_u32 s17, s30, s17
	s_bcnt1_i32_b64 s6, s[62:63]
	v_mov_b32_e32 v0, s6
	global_atomic_add v173, v0, s[16:17]

;     __device__ __forceinline__ void done(const Unit& u) const { asm volatile("s_waitcnt vmcnt(0)" ::: "memory"); if (lane0()) __hip_atomic_fetch_add(cnt + 64 * u.pm, 1u, __ATOMIC_RELAXED, __HIP_MEMORY_SCOPE_AGENT); }
; #define PG8_BAR __builtin_amdgcn_s_barrier()
; template <class Epi, class Sched, bool ALIGN_EPI = false, bool SP2 = false>
; __device__ __forceinline__ void gemm_phase(PG8_LAS unsigned char* lds, const Gemm g, const Sched& S, const Epi& E, const int tid_in) {
;     ...
;         if constexpr (!Epi::AFTER_DRAIN) { E(acc, cur, wr, wc, fr, fq); S.done(cur); }
;         if (!has_next) break;
; #pragma unroll
;         for (int a = 0; a < 2; ++a)
; #pragma unroll
;             for (int b = 0; b < 2; ++b)
; #pragma unroll
;                 for (int m = 0; m < 4; ++m)
; #pragma unroll
;                     for (int n = 0; n < 2; ++n) acc[a][b][m][n] = (f32x4){0.f, 0.f, 0.f, 0.f};
;         cur = nxt; cA = nA; cB = nB; ++ui;
;         if constexpr (ALIGN_EPI) { if (wr == 1) PG8_BAR; }
.Lgu_defer_join:
	s_andn2_b64 vcc, exec, s[56:57]
	s_mov_b64 s[22:23], -1
	s_cbranch_vccnz .LBB0_2308
	s_andn2_b64 vcc, exec, s[42:43]
	s_cbranch_vccnz .LBB0_2307
	s_barrier
	s_branch .LBB0_2307
